# ph4 up-projection GEMMs (K=384 / K=256) also use the k-block-major weights and the constant-ring-position pipelined K loop (fully unrolled there) with the DMA-free tail
# speedup vs baseline: 1.0325x; 1.0026x over previous
; #define LAS __attribute__((address_space(3)))
;   int tid = tid_in; asm volatile("" : "+v"(tid));
;   const int lane = tid & 63, wid = __builtin_amdgcn_readfirstlane(tid >> 6), wr = wid >> 1, wc = wid & 1;
;   const int m0 = mt * 128, n0 = nt * 256;
;   const int r = lane & 31, h = lane >> 5, key = (r >> 2) & 3;
;   constexpr int STG = 24576;
;   const int rowl = lane >> 2, cch = (lane & 3) ^ ((lane >> 4) & 3);
;   const unsigned voffA = (unsigned)(rowl * lda * 2 + cch * 16), voffB = (unsigned)(rowl * K * 2 + cch * 16);
;   const char* Abase = (const char*)(A + (size_t)m0 * lda) + (size_t)(wid * 2) * 32 * lda;
;   const char* Bbase = (const char*)(Bt + (size_t)n0 * K) + (size_t)(wid * 4) * 32 * K;
;   const size_t ablk = (size_t)32 * lda, bblk = (size_t)32 * K;
;   LAS char* lds = (LAS char*)smem;
;   LAS char* ldsA = lds + (wid * 2) * 1024;
;   LAS char* ldsB = lds + 8192 + (wid * 4) * 1024;
;     ...
;   const int x0 = ((0 + h) ^ key) * 16, x1 = ((2 + h) ^ key) * 16;
;   const int a_rd = (wr * 64 + r) * 64, b_rd = 8192 + (wc * 128 + r) * 64;
;   f32x16 acc[2][4];
; #pragma unroll
;   for (int i = 0; i < 2; ++i)
; #pragma unroll
;     for (int j = 0; j < 4; ++j)
; #pragma unroll
;       for (int e = 0; e < 16; ++e) acc[i][j][e] = 0.f;
;   const int nk = K >> 5;
;   DMA_STEP_(0, 0);
;   DMA_STEP_(1, STG);
;   asm volatile("s_waitcnt vmcnt(6)" ::: "memory");
;   __builtin_amdgcn_s_barrier();
;   asm volatile("" ::: "memory");
;   int s0 = 0, s2 = 2 * STG;
.LBB0_146:
	v_readlane_b32 s10, v252, 29
	s_cmp_ge_i32 s40, s10
	s_mov_b64 s[12:13], -1
	s_cbranch_scc0 .LBB0_150
	v_readlane_b32 s10, v252, 29
	s_sub_i32 s10, s40, s10
	v_mov_b32_e32 v189, v188
	s_bfe_u32 s11, s10, 0x5001a
	s_add_i32 s11, s10, s11
	v_readfirstlane_b32 s46, v189
	s_ashr_i32 s58, s46, 6
	s_sext_i32_i16 s11, s11
	s_lshl_b32 s42, s58, 2
	s_ashr_i32 s11, s11, 5
	v_readlane_b32 s12, v252, 18
	s_ashr_i32 s43, s42, 31
	s_lshl_b32 s12, s11, s12
	v_readlane_b32 s13, v252, 41
	s_lshl_b64 s[44:45], s[42:43], 10
	s_lshl_b32 s42, s58, 12
	s_add_i32 s12, s12, s13
	s_lshl_b32 s13, s40, 7
	s_lshl_b32 s11, s11, 10
	s_lshl_b32 s10, s10, 5
	s_add_i32 s43, s42, 16
	s_ashr_i32 s42, s46, 1
	s_lshl_b32 s12, s12, 10
	s_and_b32 s13, s13, 0x380
	s_sub_i32 s10, s10, s11
	v_and_b32_e32 v0, 31, v189
	s_andn2_b32 s42, s42, 63
	s_or_b32 s41, s12, s13
	s_and_b32 s12, s10, 0xffffff00
	v_or_b32_e32 v197, s42, v0
	s_lshl_b32 s42, s58, 7
	s_lshl_b32 s10, s58, 1
	s_ashr_i32 s13, s12, 31
	s_add_i32 s59, s43, 0x2000
	s_and_b32 s42, s42, 0x80
	s_mul_i32 s47, s41, 0x1200
	s_mul_hi_i32 s46, s41, 0x1200
	s_add_u32 s47, s18, s47
	s_mul_i32 s11, s58, 0x24000
	s_addc_u32 s56, s19, s46
	s_mul_hi_i32 s10, s10, 0x12000
	s_add_u32 s46, s47, s11
	s_addc_u32 s47, s56, s10
	s_lshl_b64 s[56:57], s[12:13], 6
	s_add_u32 s10, s20, s56
	s_addc_u32 s11, s21, s57
	v_bfe_u32 v5, v189, 2, 4
	v_lshlrev_b32_e32 v2, 4, v189
	s_add_u32 s56, s10, s44
	v_bitop3_b32 v6, v2, 48, v189 bitop3:0x48
	v_or_b32_e32 v2, s42, v0
	v_mul_u32_u24_e32 v0, 0x1200, v5
	s_addc_u32 s57, s11, s45
	s_lshl_b32 s10, s58, 11
	v_or_b32_e32 v0, v0, v6
	s_sub_i32 s44, s43, s10
	v_lshl_add_u64 v[192:193], s[46:47], 0, v[0:1]
	s_mov_b32 m0, s44
	s_mov_b64 s[10:11], 0x12000
	v_lshlrev_b32_e32 v218, 6, v2
	global_load_lds_dwordx4 v0, s[46:47]
	v_lshl_add_u64 v[2:3], v[192:193], 0, s[10:11]
	s_add_i32 m0, s44, 0x400
	v_lshl_or_b32 v0, v5, 9, v6
	v_lshl_or_b32 v10, v5, 6, v6
	v_mov_b32_e32 v11, 0
	global_load_lds_dwordx4 v[2:3], off
	v_lshl_add_u64 v[194:195], s[56:57], 0, v[10:11]
	s_mov_b32 m0, s59
	s_mov_b64 s[46:47], 0x2000
	global_load_lds_dwordx4 v[194:195], off
	global_load_lds_dwordx4 v[194:195], off offset:1024
	global_load_lds_dwordx4 v[194:195], off offset:2048
	global_load_lds_dwordx4 v[194:195], off offset:3072
	s_mov_b64 s[46:47], 0x4000
	s_mov_b64 s[10:11], 0x6000
	s_mov_b64 s[10:11], 0x12040
	s_add_i32 m0, s44, 0x6000
	v_lshl_add_u64 v[2:3], v[192:193], 0, 64
	global_load_lds_dwordx4 v[2:3], off
	v_lshl_add_u64 v[2:3], v[192:193], 0, s[10:11]
	s_add_i32 m0, s44, 0x6400
	s_mov_b64 s[46:47], 0x2040
	global_load_lds_dwordx4 v[2:3], off
	s_add_i32 m0, s43, 0x8000
	s_mov_b32 s100, 0x10000
	v_lshl_add_u64 v[2:3], v[194:195], 0, s[100:101]
	global_load_lds_dwordx4 v[2:3], off
	global_load_lds_dwordx4 v[2:3], off offset:1024
	global_load_lds_dwordx4 v[2:3], off offset:2048
	global_load_lds_dwordx4 v[2:3], off offset:3072
	s_mov_b64 s[46:47], 0x4040
	s_mov_b64 s[10:11], 0x6040
	v_bfe_u32 v196, v189, 5, 1
	v_bfe_u32 v5, v189, 2, 2
	v_lshrrev_b32_e32 v4, 2, v189
	s_lshl_b32 s100, s100, 1
	v_lshl_add_u64 v[194:195], v[194:195], 0, s[100:101]
	s_waitcnt vmcnt(6)
	s_barrier
	v_bitop3_b32 v2, v196, v5, 2 bitop3:0x36
	v_bitop3_b32 v0, v196, v4, 3 bitop3:0x78
	v_lshlrev_b32_e32 v220, 4, v2
	v_mov_b32_e32 v2, 0
	v_lshlrev_b32_e32 v219, 6, v197
	v_lshlrev_b32_e32 v0, 4, v0
	s_mov_b32 s46, 0xc000
	s_mov_b32 s45, 0
	s_mov_b32 s47, 0
	v_mov_b32_e32 v3, v2
	v_mov_b32_e32 v4, v2
	v_mov_b32_e32 v5, v2
	v_mov_b32_e32 v6, v2
	v_mov_b32_e32 v7, v2
	v_mov_b32_e32 v8, v2
	v_mov_b32_e32 v9, v2
	v_mov_b32_e32 v10, v2
	v_mov_b32_e32 v11, v2
	v_mov_b32_e32 v12, v2
	v_mov_b32_e32 v13, v2
	v_mov_b32_e32 v14, v2
	v_mov_b32_e32 v15, v2
	v_mov_b32_e32 v16, v2
	v_mov_b32_e32 v17, v2
	v_mov_b32_e32 v18, v2
	v_mov_b32_e32 v19, v2
	v_mov_b32_e32 v20, v2
	v_mov_b32_e32 v21, v2
	v_mov_b32_e32 v22, v2
	v_mov_b32_e32 v23, v2
	v_mov_b32_e32 v24, v2
	v_mov_b32_e32 v25, v2
	v_mov_b32_e32 v26, v2
	v_mov_b32_e32 v27, v2
	v_mov_b32_e32 v28, v2
	v_mov_b32_e32 v29, v2
	v_mov_b32_e32 v30, v2
	v_mov_b32_e32 v31, v2
	v_mov_b32_e32 v32, v2
	v_mov_b32_e32 v33, v2
	v_mov_b32_e32 v50, v2
	v_mov_b32_e32 v51, v2
	v_mov_b32_e32 v52, v2
	v_mov_b32_e32 v53, v2
	v_mov_b32_e32 v54, v2
	v_mov_b32_e32 v55, v2
	v_mov_b32_e32 v56, v2
	v_mov_b32_e32 v57, v2
	v_mov_b32_e32 v58, v2
	v_mov_b32_e32 v59, v2
	v_mov_b32_e32 v60, v2
	v_mov_b32_e32 v61, v2
	v_mov_b32_e32 v62, v2
	v_mov_b32_e32 v63, v2
	v_mov_b32_e32 v64, v2
	v_mov_b32_e32 v65, v2
	v_mov_b32_e32 v82, v2
	v_mov_b32_e32 v83, v2
	v_mov_b32_e32 v84, v2
	v_mov_b32_e32 v85, v2
	v_mov_b32_e32 v86, v2
	v_mov_b32_e32 v87, v2
	v_mov_b32_e32 v88, v2
	v_mov_b32_e32 v89, v2
	v_mov_b32_e32 v90, v2
	v_mov_b32_e32 v91, v2
	v_mov_b32_e32 v92, v2
	v_mov_b32_e32 v93, v2
	v_mov_b32_e32 v94, v2
	v_mov_b32_e32 v95, v2
	v_mov_b32_e32 v96, v2
	v_mov_b32_e32 v97, v2
	v_mov_b32_e32 v34, v2
	v_mov_b32_e32 v35, v2
	v_mov_b32_e32 v36, v2
	v_mov_b32_e32 v37, v2
	v_mov_b32_e32 v38, v2
	v_mov_b32_e32 v39, v2
	v_mov_b32_e32 v40, v2
	v_mov_b32_e32 v41, v2
	v_mov_b32_e32 v42, v2
	v_mov_b32_e32 v43, v2
	v_mov_b32_e32 v44, v2
	v_mov_b32_e32 v45, v2
	v_mov_b32_e32 v46, v2
	v_mov_b32_e32 v47, v2
	v_mov_b32_e32 v48, v2
	v_mov_b32_e32 v49, v2
	v_mov_b32_e32 v66, v2
	v_mov_b32_e32 v67, v2
	v_mov_b32_e32 v68, v2
	v_mov_b32_e32 v69, v2
	v_mov_b32_e32 v70, v2
	v_mov_b32_e32 v71, v2
	v_mov_b32_e32 v72, v2
	v_mov_b32_e32 v73, v2
	v_mov_b32_e32 v74, v2
	v_mov_b32_e32 v75, v2
	v_mov_b32_e32 v76, v2
	v_mov_b32_e32 v77, v2
	v_mov_b32_e32 v78, v2
	v_mov_b32_e32 v79, v2
	v_mov_b32_e32 v80, v2
	v_mov_b32_e32 v81, v2
	v_mov_b32_e32 v98, v2
	v_mov_b32_e32 v99, v2
; #define LAS __attribute__((address_space(3)))
; DI f32x16 mfma32(bf16x8 a, bf16x8 b, f32x16 c) { return __builtin_amdgcn_mfma_f32_32x32x16_bf16(a, b, c, 0, 0, 0); }
;     ...
;   for (int kt = 0; kt < nk; ++kt) {
;     const int kn = (kt + 2 < nk) ? (kt + 2) : (nk - 1);
;     const LAS char* cur = lds + s0;
;     bf16x8 af[2][2], bfr[2][4];
; #pragma unroll
;     for (int kk = 0; kk < 2; ++kk) {
;       const int xo = kk ? x1 : x0;
;       af[kk][0] = *(const LAS bf16x8*)(cur + a_rd + xo);
;       bfr[kk][0] = *(const LAS bf16x8*)(cur + b_rd + xo);
;       bfr[kk][1] = *(const LAS bf16x8*)(cur + b_rd + 2048 + xo);
;       af[kk][1] = *(const LAS bf16x8*)(cur + a_rd + 2048 + xo);
;       bfr[kk][2] = *(const LAS bf16x8*)(cur + b_rd + 4096 + xo);
;       bfr[kk][3] = *(const LAS bf16x8*)(cur + b_rd + 6144 + xo);
;     }
;     DMA_STEP_(kn, s2);
; #pragma unroll
;     for (int kk = 0; kk < 2; ++kk) {
;       acc[0][0] = mfma32(bfr[kk][0], af[kk][0], acc[0][0]); acc[0][1] = mfma32(bfr[kk][1], af[kk][0], acc[0][1]);
;       acc[1][0] = mfma32(bfr[kk][0], af[kk][1], acc[1][0]); acc[1][1] = mfma32(bfr[kk][1], af[kk][1], acc[1][1]);
;       acc[0][2] = mfma32(bfr[kk][2], af[kk][0], acc[0][2]); acc[0][3] = mfma32(bfr[kk][3], af[kk][0], acc[0][3]);
;       acc[1][2] = mfma32(bfr[kk][2], af[kk][1], acc[1][2]); acc[1][3] = mfma32(bfr[kk][3], af[kk][1], acc[1][3]);
;     }
;     __builtin_amdgcn_sched_group_barrier(0x100, 12, 0);
;     __builtin_amdgcn_sched_group_barrier(0x010, 6, 0);
;     __builtin_amdgcn_sched_group_barrier(0x008, 16, 0);
;     asm volatile("s_waitcnt vmcnt(6) lgkmcnt(0)" ::: "memory");
;     __builtin_amdgcn_s_barrier();
;     asm volatile("" ::: "memory");
;     s0 = (s0 == 2 * STG) ? 0 : s0 + STG;
;     s2 = (s2 == 2 * STG) ? 0 : s2 + STG;
	v_mov_b32_e32 v100, v2
	v_mov_b32_e32 v101, v2
	v_mov_b32_e32 v102, v2
	v_mov_b32_e32 v103, v2
	v_mov_b32_e32 v104, v2
	v_mov_b32_e32 v105, v2
	v_mov_b32_e32 v106, v2
	v_mov_b32_e32 v107, v2
	v_mov_b32_e32 v108, v2
	v_mov_b32_e32 v109, v2
	v_mov_b32_e32 v110, v2
	v_mov_b32_e32 v111, v2
	v_mov_b32_e32 v112, v2
	v_mov_b32_e32 v113, v2
	v_mov_b32_e32 v114, v2
	v_mov_b32_e32 v115, v2
	v_mov_b32_e32 v116, v2
	v_mov_b32_e32 v117, v2
	v_mov_b32_e32 v118, v2
	v_mov_b32_e32 v119, v2
	v_mov_b32_e32 v120, v2
	v_mov_b32_e32 v121, v2
	v_mov_b32_e32 v122, v2
	v_mov_b32_e32 v123, v2
	v_mov_b32_e32 v124, v2
	v_mov_b32_e32 v125, v2
	v_mov_b32_e32 v126, v2
	v_mov_b32_e32 v127, v2
	v_mov_b32_e32 v128, v2
	v_mov_b32_e32 v129, v2
	s_mov_b64 s[56:57], 0x2080
	s_mov_b64 s[58:59], 0x4080
	v_readfirstlane_b32 s10, v192
	v_readfirstlane_b32 s11, v193
	v_readfirstlane_b32 s100, v194
	v_readfirstlane_b32 s101, v195
	s_sub_u32 s10, s10, 0x100000
	s_subb_u32 s11, s11, 0
	s_sub_u32 s100, s100, 0x100000
	s_subb_u32 s101, s101, 0
	v_subrev_u32_e32 v238, s10, v192
	v_subrev_u32_e32 v239, s100, v194
	s_add_u32 vcc_lo, s10, s24
	s_addc_u32 vcc_hi, s11, s25
	s_add_u32 s70, s10, s36
	s_addc_u32 s71, s11, s37
	v_add3_u32 v226, v219, v0, 16
	v_add3_u32 v227, v218, v0, 16
	v_add3_u32 v228, v219, v220, 16
	v_add3_u32 v229, v218, v220, 16
	ds_read_b128 v[154:157], v226 offset:0
	ds_read_b128 v[182:185], v227 offset:8192
	ds_read_b128 v[178:181], v227 offset:10240
	ds_read_b128 v[158:161], v226 offset:2048
	ds_read_b128 v[174:177], v227 offset:12288
	ds_read_b128 v[170:173], v227 offset:14336
	s_setprio 1
.LBB0_148:
	ds_read_b128 v[138:141], v228 offset:0
	ds_read_b128 v[162:165], v229 offset:8192
	ds_read_b128 v[166:169], v229 offset:10240
	ds_read_b128 v[142:145], v228 offset:2048
	ds_read_b128 v[146:149], v229 offset:12288
	ds_read_b128 v[150:153], v229 offset:14336
	s_add_i32 m0, s44, 0xc000
	s_waitcnt lgkmcnt(6)
	v_mfma_f32_32x32x16_bf16 v[114:129], v[182:185], v[154:157], v[114:129]
	global_load_lds_dwordx4 v238, vcc
	s_add_i32 m0, s44, 0xc400
	s_add_u32 vcc_lo, vcc_lo, 64
	s_addc_u32 vcc_hi, vcc_hi, 0
	v_mfma_f32_32x32x16_bf16 v[98:113], v[178:181], v[154:157], v[98:113]
	global_load_lds_dwordx4 v238, s[70:71]
	s_add_i32 m0, s43, 0xe000
	s_add_u32 s70, s70, 64
	s_addc_u32 s71, s71, 0
	v_mfma_f32_32x32x16_bf16 v[66:81], v[182:185], v[158:161], v[66:81]
	global_load_lds_dwordx4 v239, s[100:101]
	v_mfma_f32_32x32x16_bf16 v[34:49], v[178:181], v[158:161], v[34:49]
	global_load_lds_dwordx4 v239, s[100:101] offset:1024
	v_mfma_f32_32x32x16_bf16 v[82:97], v[174:177], v[154:157], v[82:97]
	global_load_lds_dwordx4 v239, s[100:101] offset:2048
	v_mfma_f32_32x32x16_bf16 v[50:65], v[170:173], v[154:157], v[50:65]
	global_load_lds_dwordx4 v239, s[100:101] offset:3072
	s_add_u32 s100, s100, 0x10000
	s_addc_u32 s101, s101, 0
	v_mfma_f32_32x32x16_bf16 v[18:33], v[174:177], v[158:161], v[18:33]
	v_mfma_f32_32x32x16_bf16 v[2:17], v[170:173], v[158:161], v[2:17]
	s_waitcnt vmcnt(6) lgkmcnt(0)
	s_barrier
	ds_read_b128 v[154:157], v226 offset:24576
	ds_read_b128 v[182:185], v227 offset:32768
	ds_read_b128 v[178:181], v227 offset:34816
	ds_read_b128 v[158:161], v226 offset:26624
	ds_read_b128 v[174:177], v227 offset:36864
	ds_read_b128 v[170:173], v227 offset:38912
	v_mfma_f32_32x32x16_bf16 v[114:129], v[162:165], v[138:141], v[114:129]
	v_mfma_f32_32x32x16_bf16 v[98:113], v[166:169], v[138:141], v[98:113]
	v_mfma_f32_32x32x16_bf16 v[66:81], v[162:165], v[142:145], v[66:81]
	v_mfma_f32_32x32x16_bf16 v[34:49], v[166:169], v[142:145], v[34:49]
	v_mfma_f32_32x32x16_bf16 v[82:97], v[146:149], v[138:141], v[82:97]
	v_mfma_f32_32x32x16_bf16 v[50:65], v[150:153], v[138:141], v[50:65]
	v_mfma_f32_32x32x16_bf16 v[18:33], v[146:149], v[142:145], v[18:33]
	v_mfma_f32_32x32x16_bf16 v[2:17], v[150:153], v[142:145], v[2:17]
	ds_read_b128 v[138:141], v228 offset:24576
	ds_read_b128 v[162:165], v229 offset:32768
	ds_read_b128 v[166:169], v229 offset:34816
	ds_read_b128 v[142:145], v228 offset:26624
	ds_read_b128 v[146:149], v229 offset:36864
	ds_read_b128 v[150:153], v229 offset:38912
	s_add_i32 m0, s44, 0x0
	s_waitcnt lgkmcnt(6)
	v_mfma_f32_32x32x16_bf16 v[114:129], v[182:185], v[154:157], v[114:129]
	global_load_lds_dwordx4 v238, vcc
	s_add_i32 m0, s44, 0x400
	s_add_u32 vcc_lo, vcc_lo, 64
	s_addc_u32 vcc_hi, vcc_hi, 0
	v_mfma_f32_32x32x16_bf16 v[98:113], v[178:181], v[154:157], v[98:113]
	global_load_lds_dwordx4 v238, s[70:71]
	s_add_i32 m0, s43, 0x2000
	s_add_u32 s70, s70, 64
	s_addc_u32 s71, s71, 0
	v_mfma_f32_32x32x16_bf16 v[66:81], v[182:185], v[158:161], v[66:81]
	global_load_lds_dwordx4 v239, s[100:101]
	v_mfma_f32_32x32x16_bf16 v[34:49], v[178:181], v[158:161], v[34:49]
	global_load_lds_dwordx4 v239, s[100:101] offset:1024
	v_mfma_f32_32x32x16_bf16 v[82:97], v[174:177], v[154:157], v[82:97]
	global_load_lds_dwordx4 v239, s[100:101] offset:2048
	v_mfma_f32_32x32x16_bf16 v[50:65], v[170:173], v[154:157], v[50:65]
	global_load_lds_dwordx4 v239, s[100:101] offset:3072
	s_add_u32 s100, s100, 0x10000
	s_addc_u32 s101, s101, 0
	v_mfma_f32_32x32x16_bf16 v[18:33], v[174:177], v[158:161], v[18:33]
	v_mfma_f32_32x32x16_bf16 v[2:17], v[170:173], v[158:161], v[2:17]
	s_waitcnt vmcnt(6) lgkmcnt(0)
	s_barrier
; #define LAS __attribute__((address_space(3)))
; DI f32x16 mfma32(bf16x8 a, bf16x8 b, f32x16 c) { return __builtin_amdgcn_mfma_f32_32x32x16_bf16(a, b, c, 0, 0, 0); }
;     ...
;   for (int kt = 0; kt < nk; ++kt) {
;     const int kn = (kt + 2 < nk) ? (kt + 2) : (nk - 1);
;     const LAS char* cur = lds + s0;
;     bf16x8 af[2][2], bfr[2][4];
; #pragma unroll
;     for (int kk = 0; kk < 2; ++kk) {
;       const int xo = kk ? x1 : x0;
;       af[kk][0] = *(const LAS bf16x8*)(cur + a_rd + xo);
;       bfr[kk][0] = *(const LAS bf16x8*)(cur + b_rd + xo);
;       bfr[kk][1] = *(const LAS bf16x8*)(cur + b_rd + 2048 + xo);
;       af[kk][1] = *(const LAS bf16x8*)(cur + a_rd + 2048 + xo);
;       bfr[kk][2] = *(const LAS bf16x8*)(cur + b_rd + 4096 + xo);
;       bfr[kk][3] = *(const LAS bf16x8*)(cur + b_rd + 6144 + xo);
;     }
;     DMA_STEP_(kn, s2);
; #pragma unroll
;     for (int kk = 0; kk < 2; ++kk) {
;       acc[0][0] = mfma32(bfr[kk][0], af[kk][0], acc[0][0]); acc[0][1] = mfma32(bfr[kk][1], af[kk][0], acc[0][1]);
;       acc[1][0] = mfma32(bfr[kk][0], af[kk][1], acc[1][0]); acc[1][1] = mfma32(bfr[kk][1], af[kk][1], acc[1][1]);
;       acc[0][2] = mfma32(bfr[kk][2], af[kk][0], acc[0][2]); acc[0][3] = mfma32(bfr[kk][3], af[kk][0], acc[0][3]);
;       acc[1][2] = mfma32(bfr[kk][2], af[kk][1], acc[1][2]); acc[1][3] = mfma32(bfr[kk][3], af[kk][1], acc[1][3]);
;     }
;     __builtin_amdgcn_sched_group_barrier(0x100, 12, 0);
;     __builtin_amdgcn_sched_group_barrier(0x010, 6, 0);
;     __builtin_amdgcn_sched_group_barrier(0x008, 16, 0);
;     asm volatile("s_waitcnt vmcnt(6) lgkmcnt(0)" ::: "memory");
;     __builtin_amdgcn_s_barrier();
;     asm volatile("" ::: "memory");
;     s0 = (s0 == 2 * STG) ? 0 : s0 + STG;
;     s2 = (s2 == 2 * STG) ? 0 : s2 + STG;
	ds_read_b128 v[154:157], v226 offset:49152
	ds_read_b128 v[182:185], v227 offset:57344
	ds_read_b128 v[178:181], v227 offset:59392
	ds_read_b128 v[158:161], v226 offset:51200
	ds_read_b128 v[174:177], v227 offset:61440
	ds_read_b128 v[170:173], v227 offset:63488
	v_mfma_f32_32x32x16_bf16 v[114:129], v[162:165], v[138:141], v[114:129]
	v_mfma_f32_32x32x16_bf16 v[98:113], v[166:169], v[138:141], v[98:113]
	v_mfma_f32_32x32x16_bf16 v[66:81], v[162:165], v[142:145], v[66:81]
	v_mfma_f32_32x32x16_bf16 v[34:49], v[166:169], v[142:145], v[34:49]
	v_mfma_f32_32x32x16_bf16 v[82:97], v[146:149], v[138:141], v[82:97]
	v_mfma_f32_32x32x16_bf16 v[50:65], v[150:153], v[138:141], v[50:65]
	v_mfma_f32_32x32x16_bf16 v[18:33], v[146:149], v[142:145], v[18:33]
	v_mfma_f32_32x32x16_bf16 v[2:17], v[150:153], v[142:145], v[2:17]
	ds_read_b128 v[138:141], v228 offset:49152
	ds_read_b128 v[162:165], v229 offset:57344
	ds_read_b128 v[166:169], v229 offset:59392
	ds_read_b128 v[142:145], v228 offset:51200
	ds_read_b128 v[146:149], v229 offset:61440
	ds_read_b128 v[150:153], v229 offset:63488
	s_add_i32 m0, s44, 0x6000
	s_waitcnt lgkmcnt(6)
	v_mfma_f32_32x32x16_bf16 v[114:129], v[182:185], v[154:157], v[114:129]
	global_load_lds_dwordx4 v238, vcc
	s_add_i32 m0, s44, 0x6400
	s_add_u32 vcc_lo, vcc_lo, 64
	s_addc_u32 vcc_hi, vcc_hi, 0
	v_mfma_f32_32x32x16_bf16 v[98:113], v[178:181], v[154:157], v[98:113]
	global_load_lds_dwordx4 v238, s[70:71]
	s_add_i32 m0, s43, 0x8000
	s_add_u32 s70, s70, 64
	s_addc_u32 s71, s71, 0
	v_mfma_f32_32x32x16_bf16 v[66:81], v[182:185], v[158:161], v[66:81]
	global_load_lds_dwordx4 v239, s[100:101]
	v_mfma_f32_32x32x16_bf16 v[34:49], v[178:181], v[158:161], v[34:49]
	global_load_lds_dwordx4 v239, s[100:101] offset:1024
	v_mfma_f32_32x32x16_bf16 v[82:97], v[174:177], v[154:157], v[82:97]
	global_load_lds_dwordx4 v239, s[100:101] offset:2048
	v_mfma_f32_32x32x16_bf16 v[50:65], v[170:173], v[154:157], v[50:65]
	global_load_lds_dwordx4 v239, s[100:101] offset:3072
	s_add_u32 s100, s100, 0x10000
	s_addc_u32 s101, s101, 0
	v_mfma_f32_32x32x16_bf16 v[18:33], v[174:177], v[158:161], v[18:33]
	v_mfma_f32_32x32x16_bf16 v[2:17], v[170:173], v[158:161], v[2:17]
	s_waitcnt vmcnt(6) lgkmcnt(0)
	s_barrier
	ds_read_b128 v[154:157], v226 offset:0
	ds_read_b128 v[182:185], v227 offset:8192
	ds_read_b128 v[178:181], v227 offset:10240
	ds_read_b128 v[158:161], v226 offset:2048
	ds_read_b128 v[174:177], v227 offset:12288
	ds_read_b128 v[170:173], v227 offset:14336
	v_mfma_f32_32x32x16_bf16 v[114:129], v[162:165], v[138:141], v[114:129]
	v_mfma_f32_32x32x16_bf16 v[98:113], v[166:169], v[138:141], v[98:113]
	v_mfma_f32_32x32x16_bf16 v[66:81], v[162:165], v[142:145], v[66:81]
	v_mfma_f32_32x32x16_bf16 v[34:49], v[166:169], v[142:145], v[34:49]
	v_mfma_f32_32x32x16_bf16 v[82:97], v[146:149], v[138:141], v[82:97]
	v_mfma_f32_32x32x16_bf16 v[50:65], v[150:153], v[138:141], v[50:65]
	v_mfma_f32_32x32x16_bf16 v[18:33], v[146:149], v[142:145], v[18:33]
	v_mfma_f32_32x32x16_bf16 v[2:17], v[150:153], v[142:145], v[2:17]
	ds_read_b128 v[138:141], v228 offset:0
	ds_read_b128 v[162:165], v229 offset:8192
	ds_read_b128 v[166:169], v229 offset:10240
	ds_read_b128 v[142:145], v228 offset:2048
	ds_read_b128 v[146:149], v229 offset:12288
	ds_read_b128 v[150:153], v229 offset:14336
	s_add_i32 m0, s44, 0xc000
	s_waitcnt lgkmcnt(6)
	v_mfma_f32_32x32x16_bf16 v[114:129], v[182:185], v[154:157], v[114:129]
	global_load_lds_dwordx4 v238, vcc
	s_add_i32 m0, s44, 0xc400
	s_add_u32 vcc_lo, vcc_lo, 64
	s_addc_u32 vcc_hi, vcc_hi, 0
	v_mfma_f32_32x32x16_bf16 v[98:113], v[178:181], v[154:157], v[98:113]
	global_load_lds_dwordx4 v238, s[70:71]
	s_add_i32 m0, s43, 0xe000
	s_add_u32 s70, s70, 64
	s_addc_u32 s71, s71, 0
	v_mfma_f32_32x32x16_bf16 v[66:81], v[182:185], v[158:161], v[66:81]
	global_load_lds_dwordx4 v239, s[100:101]
	v_mfma_f32_32x32x16_bf16 v[34:49], v[178:181], v[158:161], v[34:49]
	global_load_lds_dwordx4 v239, s[100:101] offset:1024
	v_mfma_f32_32x32x16_bf16 v[82:97], v[174:177], v[154:157], v[82:97]
	global_load_lds_dwordx4 v239, s[100:101] offset:2048
	v_mfma_f32_32x32x16_bf16 v[50:65], v[170:173], v[154:157], v[50:65]
	global_load_lds_dwordx4 v239, s[100:101] offset:3072
	s_add_u32 s100, s100, 0x10000
	s_addc_u32 s101, s101, 0
	v_mfma_f32_32x32x16_bf16 v[18:33], v[174:177], v[158:161], v[18:33]
	v_mfma_f32_32x32x16_bf16 v[2:17], v[170:173], v[158:161], v[2:17]
	s_waitcnt vmcnt(6) lgkmcnt(0)
	s_barrier
	ds_read_b128 v[154:157], v226 offset:24576
	ds_read_b128 v[182:185], v227 offset:32768
	ds_read_b128 v[178:181], v227 offset:34816
	ds_read_b128 v[158:161], v226 offset:26624
	ds_read_b128 v[174:177], v227 offset:36864
	ds_read_b128 v[170:173], v227 offset:38912
	v_mfma_f32_32x32x16_bf16 v[114:129], v[162:165], v[138:141], v[114:129]
	v_mfma_f32_32x32x16_bf16 v[98:113], v[166:169], v[138:141], v[98:113]
	v_mfma_f32_32x32x16_bf16 v[66:81], v[162:165], v[142:145], v[66:81]
	v_mfma_f32_32x32x16_bf16 v[34:49], v[166:169], v[142:145], v[34:49]
	v_mfma_f32_32x32x16_bf16 v[82:97], v[146:149], v[138:141], v[82:97]
	v_mfma_f32_32x32x16_bf16 v[50:65], v[150:153], v[138:141], v[50:65]
	v_mfma_f32_32x32x16_bf16 v[18:33], v[146:149], v[142:145], v[18:33]
	v_mfma_f32_32x32x16_bf16 v[2:17], v[150:153], v[142:145], v[2:17]
	ds_read_b128 v[138:141], v228 offset:24576
	ds_read_b128 v[162:165], v229 offset:32768
	ds_read_b128 v[166:169], v229 offset:34816
	ds_read_b128 v[142:145], v228 offset:26624
	ds_read_b128 v[146:149], v229 offset:36864
	ds_read_b128 v[150:153], v229 offset:38912
	s_add_i32 m0, s44, 0x0
	s_waitcnt lgkmcnt(6)
	v_mfma_f32_32x32x16_bf16 v[114:129], v[182:185], v[154:157], v[114:129]
	global_load_lds_dwordx4 v238, vcc
	s_add_i32 m0, s44, 0x400
	s_add_u32 vcc_lo, vcc_lo, 64
	s_addc_u32 vcc_hi, vcc_hi, 0
	v_mfma_f32_32x32x16_bf16 v[98:113], v[178:181], v[154:157], v[98:113]
	global_load_lds_dwordx4 v238, s[70:71]
	s_add_i32 m0, s43, 0x2000
	s_add_u32 s70, s70, 64
	s_addc_u32 s71, s71, 0
	v_mfma_f32_32x32x16_bf16 v[66:81], v[182:185], v[158:161], v[66:81]
	global_load_lds_dwordx4 v239, s[100:101]
	v_mfma_f32_32x32x16_bf16 v[34:49], v[178:181], v[158:161], v[34:49]
	global_load_lds_dwordx4 v239, s[100:101] offset:1024
	v_mfma_f32_32x32x16_bf16 v[82:97], v[174:177], v[154:157], v[82:97]
	global_load_lds_dwordx4 v239, s[100:101] offset:2048
	v_mfma_f32_32x32x16_bf16 v[50:65], v[170:173], v[154:157], v[50:65]
	global_load_lds_dwordx4 v239, s[100:101] offset:3072
	s_add_u32 s100, s100, 0x10000
	s_addc_u32 s101, s101, 0
	v_mfma_f32_32x32x16_bf16 v[18:33], v[174:177], v[158:161], v[18:33]
	v_mfma_f32_32x32x16_bf16 v[2:17], v[170:173], v[158:161], v[2:17]
	s_waitcnt vmcnt(6) lgkmcnt(0)
	s_barrier
; #define LAS __attribute__((address_space(3)))
; DI unsigned pk2(float a, float b) { f32x2 v = {a, b}; bf2_t r = __builtin_convertvector(v, bf2_t); return __builtin_bit_cast(unsigned, r); }
;     ...
;   for (int kt = 0; kt < nk; ++kt) {
;     const int kn = (kt + 2 < nk) ? (kt + 2) : (nk - 1);
;     const LAS char* cur = lds + s0;
;     bf16x8 af[2][2], bfr[2][4];
; #pragma unroll
;     for (int kk = 0; kk < 2; ++kk) {
;       const int xo = kk ? x1 : x0;
;       af[kk][0] = *(const LAS bf16x8*)(cur + a_rd + xo);
;       bfr[kk][0] = *(const LAS bf16x8*)(cur + b_rd + xo);
;       bfr[kk][1] = *(const LAS bf16x8*)(cur + b_rd + 2048 + xo);
;       af[kk][1] = *(const LAS bf16x8*)(cur + a_rd + 2048 + xo);
;       bfr[kk][2] = *(const LAS bf16x8*)(cur + b_rd + 4096 + xo);
;       bfr[kk][3] = *(const LAS bf16x8*)(cur + b_rd + 6144 + xo);
;     }
;     DMA_STEP_(kn, s2);
; #pragma unroll
;     for (int kk = 0; kk < 2; ++kk) {
;       acc[0][0] = mfma32(bfr[kk][0], af[kk][0], acc[0][0]); acc[0][1] = mfma32(bfr[kk][1], af[kk][0], acc[0][1]);
;       acc[1][0] = mfma32(bfr[kk][0], af[kk][1], acc[1][0]); acc[1][1] = mfma32(bfr[kk][1], af[kk][1], acc[1][1]);
;       acc[0][2] = mfma32(bfr[kk][2], af[kk][0], acc[0][2]); acc[0][3] = mfma32(bfr[kk][3], af[kk][0], acc[0][3]);
;       acc[1][2] = mfma32(bfr[kk][2], af[kk][1], acc[1][2]); acc[1][3] = mfma32(bfr[kk][3], af[kk][1], acc[1][3]);
;     }
;     __builtin_amdgcn_sched_group_barrier(0x100, 12, 0);
;     __builtin_amdgcn_sched_group_barrier(0x010, 6, 0);
;     __builtin_amdgcn_sched_group_barrier(0x008, 16, 0);
;     asm volatile("s_waitcnt vmcnt(6) lgkmcnt(0)" ::: "memory");
;     __builtin_amdgcn_s_barrier();
;     asm volatile("" ::: "memory");
;     s0 = (s0 == 2 * STG) ? 0 : s0 + STG;
;     s2 = (s2 == 2 * STG) ? 0 : s2 + STG;
;   }
;   asm volatile("s_waitcnt vmcnt(0)" ::: "memory");
;   __builtin_amdgcn_s_barrier();
;   asm volatile("" ::: "memory");
;     ...
;   {
;     const int h = lane >> 5, cl = lane & 31;
; #pragma unroll
;     for (int i = 0; i < 2; ++i)
; #pragma unroll
;       for (int j = 0; j < 4; ++j)
; #pragma unroll
;         for (int g = 0; g < 4; ++g) {
;           u32x2 w; w.x = pk2(acc[i][j][4 * g], acc[i][j][4 * g + 1]); w.y = pk2(acc[i][j][4 * g + 2], acc[i][j][4 * g + 3]);
;           *(u32x2*)(smem + (wr * 64 + i * 32 + cl) * 528 + (wc * 128 + j * 32 + 8 * g + 4 * h) * 2) = w;
	ds_read_b128 v[154:157], v226 offset:49152
	ds_read_b128 v[182:185], v227 offset:57344
	ds_read_b128 v[178:181], v227 offset:59392
	ds_read_b128 v[158:161], v226 offset:51200
	ds_read_b128 v[174:177], v227 offset:61440
	ds_read_b128 v[170:173], v227 offset:63488
	v_mfma_f32_32x32x16_bf16 v[114:129], v[162:165], v[138:141], v[114:129]
	v_mfma_f32_32x32x16_bf16 v[98:113], v[166:169], v[138:141], v[98:113]
	v_mfma_f32_32x32x16_bf16 v[66:81], v[162:165], v[142:145], v[66:81]
	v_mfma_f32_32x32x16_bf16 v[34:49], v[166:169], v[142:145], v[34:49]
	v_mfma_f32_32x32x16_bf16 v[82:97], v[146:149], v[138:141], v[82:97]
	v_mfma_f32_32x32x16_bf16 v[50:65], v[150:153], v[138:141], v[50:65]
	v_mfma_f32_32x32x16_bf16 v[18:33], v[146:149], v[142:145], v[18:33]
	v_mfma_f32_32x32x16_bf16 v[2:17], v[150:153], v[142:145], v[2:17]
	ds_read_b128 v[138:141], v228 offset:49152
	ds_read_b128 v[162:165], v229 offset:57344
	ds_read_b128 v[166:169], v229 offset:59392
	ds_read_b128 v[142:145], v228 offset:51200
	ds_read_b128 v[146:149], v229 offset:61440
	ds_read_b128 v[150:153], v229 offset:63488
	s_add_i32 m0, s44, 0x6000
	s_waitcnt lgkmcnt(6)
	v_mfma_f32_32x32x16_bf16 v[114:129], v[182:185], v[154:157], v[114:129]
	global_load_lds_dwordx4 v238, vcc
	s_add_i32 m0, s44, 0x6400
	s_add_u32 vcc_lo, vcc_lo, 64
	s_addc_u32 vcc_hi, vcc_hi, 0
	v_mfma_f32_32x32x16_bf16 v[98:113], v[178:181], v[154:157], v[98:113]
	global_load_lds_dwordx4 v238, s[70:71]
	s_add_i32 m0, s43, 0x8000
	s_add_u32 s70, s70, 64
	s_addc_u32 s71, s71, 0
	v_mfma_f32_32x32x16_bf16 v[66:81], v[182:185], v[158:161], v[66:81]
	global_load_lds_dwordx4 v239, s[100:101]
	v_mfma_f32_32x32x16_bf16 v[34:49], v[178:181], v[158:161], v[34:49]
	global_load_lds_dwordx4 v239, s[100:101] offset:1024
	v_mfma_f32_32x32x16_bf16 v[82:97], v[174:177], v[154:157], v[82:97]
	global_load_lds_dwordx4 v239, s[100:101] offset:2048
	v_mfma_f32_32x32x16_bf16 v[50:65], v[170:173], v[154:157], v[50:65]
	global_load_lds_dwordx4 v239, s[100:101] offset:3072
	s_add_u32 s100, s100, 0x10000
	s_addc_u32 s101, s101, 0
	v_mfma_f32_32x32x16_bf16 v[18:33], v[174:177], v[158:161], v[18:33]
	v_mfma_f32_32x32x16_bf16 v[2:17], v[170:173], v[158:161], v[2:17]
	s_waitcnt vmcnt(6) lgkmcnt(0)
	s_barrier
	ds_read_b128 v[154:157], v226 offset:0
	ds_read_b128 v[182:185], v227 offset:8192
	ds_read_b128 v[178:181], v227 offset:10240
	ds_read_b128 v[158:161], v226 offset:2048
	ds_read_b128 v[174:177], v227 offset:12288
	ds_read_b128 v[170:173], v227 offset:14336
	v_mfma_f32_32x32x16_bf16 v[114:129], v[162:165], v[138:141], v[114:129]
	v_mfma_f32_32x32x16_bf16 v[98:113], v[166:169], v[138:141], v[98:113]
	v_mfma_f32_32x32x16_bf16 v[66:81], v[162:165], v[142:145], v[66:81]
	v_mfma_f32_32x32x16_bf16 v[34:49], v[166:169], v[142:145], v[34:49]
	v_mfma_f32_32x32x16_bf16 v[82:97], v[146:149], v[138:141], v[82:97]
	v_mfma_f32_32x32x16_bf16 v[50:65], v[150:153], v[138:141], v[50:65]
	v_mfma_f32_32x32x16_bf16 v[18:33], v[146:149], v[142:145], v[18:33]
	v_mfma_f32_32x32x16_bf16 v[2:17], v[150:153], v[142:145], v[2:17]
	s_add_i32 s45, s45, 6
	s_cmp_lg_u32 s45, 6
	s_cbranch_scc1 .LBB0_148
	ds_read_b128 v[138:141], v228 offset:0
	ds_read_b128 v[162:165], v229 offset:8192
	ds_read_b128 v[166:169], v229 offset:10240
	ds_read_b128 v[142:145], v228 offset:2048
	ds_read_b128 v[146:149], v229 offset:12288
	ds_read_b128 v[150:153], v229 offset:14336
	s_waitcnt lgkmcnt(6)
	v_mfma_f32_32x32x16_bf16 v[114:129], v[182:185], v[154:157], v[114:129]
	v_mfma_f32_32x32x16_bf16 v[98:113], v[178:181], v[154:157], v[98:113]
	v_mfma_f32_32x32x16_bf16 v[66:81], v[182:185], v[158:161], v[66:81]
	v_mfma_f32_32x32x16_bf16 v[34:49], v[178:181], v[158:161], v[34:49]
	v_mfma_f32_32x32x16_bf16 v[82:97], v[174:177], v[154:157], v[82:97]
	v_mfma_f32_32x32x16_bf16 v[50:65], v[170:173], v[154:157], v[50:65]
	v_mfma_f32_32x32x16_bf16 v[18:33], v[174:177], v[158:161], v[18:33]
	v_mfma_f32_32x32x16_bf16 v[2:17], v[170:173], v[158:161], v[2:17]
	s_waitcnt vmcnt(0) lgkmcnt(0)
	s_barrier
	ds_read_b128 v[154:157], v226 offset:24576
	ds_read_b128 v[182:185], v227 offset:32768
	ds_read_b128 v[178:181], v227 offset:34816
	ds_read_b128 v[158:161], v226 offset:26624
	ds_read_b128 v[174:177], v227 offset:36864
	ds_read_b128 v[170:173], v227 offset:38912
	v_mfma_f32_32x32x16_bf16 v[114:129], v[162:165], v[138:141], v[114:129]
	v_mfma_f32_32x32x16_bf16 v[98:113], v[166:169], v[138:141], v[98:113]
	v_mfma_f32_32x32x16_bf16 v[66:81], v[162:165], v[142:145], v[66:81]
	v_mfma_f32_32x32x16_bf16 v[34:49], v[166:169], v[142:145], v[34:49]
	v_mfma_f32_32x32x16_bf16 v[82:97], v[146:149], v[138:141], v[82:97]
	v_mfma_f32_32x32x16_bf16 v[50:65], v[150:153], v[138:141], v[50:65]
	v_mfma_f32_32x32x16_bf16 v[18:33], v[146:149], v[142:145], v[18:33]
	v_mfma_f32_32x32x16_bf16 v[2:17], v[150:153], v[142:145], v[2:17]
	ds_read_b128 v[138:141], v228 offset:24576
	ds_read_b128 v[162:165], v229 offset:32768
	ds_read_b128 v[166:169], v229 offset:34816
	ds_read_b128 v[142:145], v228 offset:26624
	ds_read_b128 v[146:149], v229 offset:36864
	ds_read_b128 v[150:153], v229 offset:38912
	s_waitcnt lgkmcnt(6)
	v_mfma_f32_32x32x16_bf16 v[114:129], v[182:185], v[154:157], v[114:129]
	v_mfma_f32_32x32x16_bf16 v[98:113], v[178:181], v[154:157], v[98:113]
	v_mfma_f32_32x32x16_bf16 v[66:81], v[182:185], v[158:161], v[66:81]
	v_mfma_f32_32x32x16_bf16 v[34:49], v[178:181], v[158:161], v[34:49]
	v_mfma_f32_32x32x16_bf16 v[82:97], v[174:177], v[154:157], v[82:97]
	v_mfma_f32_32x32x16_bf16 v[50:65], v[170:173], v[154:157], v[50:65]
	v_mfma_f32_32x32x16_bf16 v[18:33], v[174:177], v[158:161], v[18:33]
	v_mfma_f32_32x32x16_bf16 v[2:17], v[170:173], v[158:161], v[2:17]
	s_waitcnt lgkmcnt(0)
	v_mfma_f32_32x32x16_bf16 v[114:129], v[162:165], v[138:141], v[114:129]
	v_mfma_f32_32x32x16_bf16 v[98:113], v[166:169], v[138:141], v[98:113]
	v_mfma_f32_32x32x16_bf16 v[66:81], v[162:165], v[142:145], v[66:81]
	v_mfma_f32_32x32x16_bf16 v[34:49], v[166:169], v[142:145], v[34:49]
	v_mfma_f32_32x32x16_bf16 v[82:97], v[146:149], v[138:141], v[82:97]
	v_mfma_f32_32x32x16_bf16 v[50:65], v[150:153], v[138:141], v[50:65]
	v_mfma_f32_32x32x16_bf16 v[18:33], v[146:149], v[142:145], v[18:33]
	v_mfma_f32_32x32x16_bf16 v[2:17], v[150:153], v[142:145], v[2:17]
	s_waitcnt lgkmcnt(0)
	s_mov_b32 s101, 0
	s_mov_b32 s71, 0
	s_setprio 0
	v_mul_lo_u32 v0, v197, s55
	v_add_u32_e32 v0, 16, v0
	s_nop 1
	v_cvt_pk_bf16_f32 v114, v114, v115
	v_cvt_pk_bf16_f32 v115, v116, v117
	v_lshlrev_b32_e32 v116, 3, v196
	s_lshl_b32 s10, s42, 1
	v_add3_u32 v0, v0, v116, s10
	v_cvt_pk_bf16_f32 v116, v118, v119
	v_cvt_pk_bf16_f32 v117, v120, v121
	v_cvt_pk_bf16_f32 v98, v98, v99
	v_cvt_pk_bf16_f32 v99, v100, v101
	v_cvt_pk_bf16_f32 v100, v102, v103
	v_cvt_pk_bf16_f32 v101, v104, v105
	v_cvt_pk_bf16_f32 v82, v82, v83
	v_cvt_pk_bf16_f32 v83, v84, v85
	v_cvt_pk_bf16_f32 v84, v86, v87
	v_cvt_pk_bf16_f32 v85, v88, v89
	v_cvt_pk_bf16_f32 v50, v50, v51
	v_cvt_pk_bf16_f32 v51, v52, v53
	v_cvt_pk_bf16_f32 v52, v54, v55
	v_cvt_pk_bf16_f32 v53, v56, v57
	s_waitcnt vmcnt(0)
	s_barrier
; #define GAS __attribute__((address_space(1)))
; DI unsigned pk2(float a, float b) { f32x2 v = {a, b}; bf2_t r = __builtin_convertvector(v, bf2_t); return __builtin_bit_cast(unsigned, r); }
;     ...
;   {
;     const int h = lane >> 5, cl = lane & 31;
; #pragma unroll
;     for (int i = 0; i < 2; ++i)
; #pragma unroll
;       for (int j = 0; j < 4; ++j)
; #pragma unroll
;         for (int g = 0; g < 4; ++g) {
;           u32x2 w; w.x = pk2(acc[i][j][4 * g], acc[i][j][4 * g + 1]); w.y = pk2(acc[i][j][4 * g + 2], acc[i][j][4 * g + 3]);
;           *(u32x2*)(smem + (wr * 64 + i * 32 + cl) * 528 + (wc * 128 + j * 32 + 8 * g + 4 * h) * 2) = w;
;         }
;   }
;   __syncthreads();
;   int tid2 = tid; asm volatile("" : "+v"(tid2));
;   if (EPI == 0) {
; #pragma unroll
;     for (int i = 0; i < 16; ++i) {
;       const int id = tid2 + 256 * i, r = id >> 5, c8 = (id & 31) * 8;
;       const u32x4 v = *(const u32x4*)(smem + r * 528 + c8 * 2);
;       *(GAS u32x4*)(ea.out + (size_t)(m0 + r) * ea.ldo + n0 + c8) = v;
;     }
	ds_write2_b64 v0, v[114:115], v[116:117] offset1:2
	v_cvt_pk_bf16_f32 v114, v122, v123
	v_cvt_pk_bf16_f32 v115, v124, v125
	v_cvt_pk_bf16_f32 v116, v126, v127
	v_cvt_pk_bf16_f32 v117, v128, v129
	ds_write2_b64 v0, v[98:99], v[100:101] offset0:8 offset1:10
	v_cvt_pk_bf16_f32 v98, v106, v107
	v_cvt_pk_bf16_f32 v99, v108, v109
	v_cvt_pk_bf16_f32 v100, v110, v111
	v_cvt_pk_bf16_f32 v101, v112, v113
	ds_write2_b64 v0, v[82:83], v[84:85] offset0:16 offset1:18
	v_cvt_pk_bf16_f32 v82, v90, v91
	v_cvt_pk_bf16_f32 v83, v92, v93
	v_cvt_pk_bf16_f32 v84, v94, v95
	v_cvt_pk_bf16_f32 v85, v96, v97
	ds_write2_b64 v0, v[50:51], v[52:53] offset0:24 offset1:26
	v_cvt_pk_bf16_f32 v50, v58, v59
	v_cvt_pk_bf16_f32 v51, v60, v61
	v_cvt_pk_bf16_f32 v52, v62, v63
	v_cvt_pk_bf16_f32 v53, v64, v65
	ds_write2_b64 v0, v[114:115], v[116:117] offset0:4 offset1:6
	ds_write2_b64 v0, v[98:99], v[100:101] offset0:12 offset1:14
	ds_write2_b64 v0, v[82:83], v[84:85] offset0:20 offset1:22
	ds_write2_b64 v0, v[50:51], v[52:53] offset0:28 offset1:30
	v_cvt_pk_bf16_f32 v50, v66, v67
	v_cvt_pk_bf16_f32 v51, v68, v69
	v_cvt_pk_bf16_f32 v52, v70, v71
	v_cvt_pk_bf16_f32 v53, v72, v73
	v_add_u32_e32 v0, 0x4000, v0
	v_cvt_pk_bf16_f32 v34, v34, v35
	v_cvt_pk_bf16_f32 v35, v36, v37
	v_cvt_pk_bf16_f32 v36, v38, v39
	v_cvt_pk_bf16_f32 v37, v40, v41
	v_cvt_pk_bf16_f32 v18, v18, v19
	v_cvt_pk_bf16_f32 v19, v20, v21
	v_cvt_pk_bf16_f32 v20, v22, v23
	v_cvt_pk_bf16_f32 v21, v24, v25
	v_cvt_pk_bf16_f32 v2, v2, v3
	v_cvt_pk_bf16_f32 v3, v4, v5
	v_cvt_pk_bf16_f32 v4, v6, v7
	v_cvt_pk_bf16_f32 v5, v8, v9
	ds_write2_b64 v0, v[50:51], v[52:53] offset0:64 offset1:66
	v_cvt_pk_bf16_f32 v50, v74, v75
	v_cvt_pk_bf16_f32 v51, v76, v77
	v_cvt_pk_bf16_f32 v52, v78, v79
	v_cvt_pk_bf16_f32 v53, v80, v81
	ds_write2_b64 v0, v[34:35], v[36:37] offset0:72 offset1:74
	v_cvt_pk_bf16_f32 v34, v42, v43
	v_cvt_pk_bf16_f32 v35, v44, v45
	v_cvt_pk_bf16_f32 v36, v46, v47
	v_cvt_pk_bf16_f32 v37, v48, v49
	ds_write2_b64 v0, v[18:19], v[20:21] offset0:80 offset1:82
	v_cvt_pk_bf16_f32 v18, v26, v27
	v_cvt_pk_bf16_f32 v19, v28, v29
	v_cvt_pk_bf16_f32 v20, v30, v31
	v_cvt_pk_bf16_f32 v21, v32, v33
	ds_write2_b64 v0, v[2:3], v[4:5] offset0:88 offset1:90
	v_cvt_pk_bf16_f32 v2, v10, v11
	v_cvt_pk_bf16_f32 v3, v12, v13
	v_cvt_pk_bf16_f32 v4, v14, v15
	v_cvt_pk_bf16_f32 v5, v16, v17
	s_lshl_b64 s[12:13], s[12:13], 1
	ds_write2_b64 v0, v[50:51], v[52:53] offset0:68 offset1:70
	ds_write2_b64 v0, v[34:35], v[36:37] offset0:76 offset1:78
	ds_write2_b64 v0, v[18:19], v[20:21] offset0:84 offset1:86
	ds_write2_b64 v0, v[2:3], v[4:5] offset0:92 offset1:94
	s_waitcnt vmcnt(0) lgkmcnt(0)
	s_barrier
	s_add_u32 s12, s16, s12
	v_lshlrev_b32_e32 v0, 4, v189
	v_and_b32_e32 v0, 0x1f0, v0
	s_addc_u32 s13, s17, s13
	v_add_u32_e32 v10, 16, v0
	v_lshl_add_u64 v[12:13], s[12:13], 0, v[0:1]
	v_ashrrev_i32_e32 v0, 5, v189
	v_mad_u64_u32 v[2:3], s[12:13], v0, s55, v[10:11]
	ds_read_b128 v[2:5], v2
	v_add_u32_e32 v6, s41, v0
	v_ashrrev_i32_e32 v7, 31, v6
	v_add_u32_e32 v0, 0x100, v189
	v_lshlrev_b64 v[6:7], 11, v[6:7]
	v_ashrrev_i32_e32 v0, 5, v0
	v_lshl_add_u64 v[14:15], v[12:13], 0, v[6:7]
	v_mad_u64_u32 v[6:7], s[12:13], v0, s55, v[10:11]
	ds_read_b128 v[6:9], v6
	s_waitcnt lgkmcnt(1)
	global_store_dwordx4 v[14:15], v[2:5], off
	v_readlane_b32 s44, v250, 17
	s_nop 0
	v_add_u32_e32 v2, s41, v0
	v_ashrrev_i32_e32 v3, 31, v2
	v_lshlrev_b64 v[2:3], 11, v[2:3]
	v_add_u32_e32 v0, 0x200, v189
	v_lshl_add_u64 v[2:3], v[12:13], 0, v[2:3]
	v_ashrrev_i32_e32 v0, 5, v0
	s_waitcnt lgkmcnt(0)
	global_store_dwordx4 v[2:3], v[6:9], off
	v_mad_u64_u32 v[2:3], s[12:13], v0, s55, v[10:11]
	ds_read_b128 v[2:5], v2
	v_add_u32_e32 v6, s41, v0
	v_ashrrev_i32_e32 v7, 31, v6
	v_add_u32_e32 v0, 0x300, v189
	v_lshlrev_b64 v[6:7], 11, v[6:7]
	v_ashrrev_i32_e32 v0, 5, v0
	v_lshl_add_u64 v[14:15], v[12:13], 0, v[6:7]
	v_mad_u64_u32 v[6:7], s[12:13], v0, s55, v[10:11]
	ds_read_b128 v[6:9], v6
	s_waitcnt lgkmcnt(1)
	global_store_dwordx4 v[14:15], v[2:5], off
	s_nop 1
	v_add_u32_e32 v2, s41, v0
	v_ashrrev_i32_e32 v3, 31, v2
	v_lshlrev_b64 v[2:3], 11, v[2:3]
	v_add_u32_e32 v0, 0x400, v189
	v_lshl_add_u64 v[2:3], v[12:13], 0, v[2:3]
	v_ashrrev_i32_e32 v0, 5, v0
	s_waitcnt lgkmcnt(0)
	global_store_dwordx4 v[2:3], v[6:9], off
	v_mad_u64_u32 v[2:3], s[12:13], v0, s55, v[10:11]
	ds_read_b128 v[2:5], v2
	v_add_u32_e32 v6, s41, v0
	v_ashrrev_i32_e32 v7, 31, v6
	v_add_u32_e32 v0, 0x500, v189
	v_lshlrev_b64 v[6:7], 11, v[6:7]
	v_ashrrev_i32_e32 v0, 5, v0
	v_lshl_add_u64 v[14:15], v[12:13], 0, v[6:7]
	v_mad_u64_u32 v[6:7], s[12:13], v0, s55, v[10:11]
	ds_read_b128 v[6:9], v6
	s_waitcnt lgkmcnt(1)
	global_store_dwordx4 v[14:15], v[2:5], off
	s_nop 1
	v_add_u32_e32 v2, s41, v0
	v_ashrrev_i32_e32 v3, 31, v2
	v_lshlrev_b64 v[2:3], 11, v[2:3]
	v_add_u32_e32 v0, 0x600, v189
	v_lshl_add_u64 v[2:3], v[12:13], 0, v[2:3]
	v_ashrrev_i32_e32 v0, 5, v0
	s_waitcnt lgkmcnt(0)
	global_store_dwordx4 v[2:3], v[6:9], off
	v_mad_u64_u32 v[2:3], s[12:13], v0, s55, v[10:11]
	ds_read_b128 v[2:5], v2
	v_add_u32_e32 v6, s41, v0
	v_ashrrev_i32_e32 v7, 31, v6
	v_add_u32_e32 v0, 0x700, v189
	v_lshlrev_b64 v[6:7], 11, v[6:7]
	v_ashrrev_i32_e32 v0, 5, v0
	v_lshl_add_u64 v[14:15], v[12:13], 0, v[6:7]
	v_mad_u64_u32 v[6:7], s[12:13], v0, s55, v[10:11]
	ds_read_b128 v[6:9], v6
	s_waitcnt lgkmcnt(1)
	global_store_dwordx4 v[14:15], v[2:5], off
	s_nop 1
	v_add_u32_e32 v2, s41, v0
	v_ashrrev_i32_e32 v3, 31, v2
	v_lshlrev_b64 v[2:3], 11, v[2:3]
	v_add_u32_e32 v0, 0x800, v189
	v_lshl_add_u64 v[2:3], v[12:13], 0, v[2:3]
	v_ashrrev_i32_e32 v0, 5, v0
	s_waitcnt lgkmcnt(0)
; #define LAS __attribute__((address_space(3)))
;   int tid = tid_in; asm volatile("" : "+v"(tid));
;   const int lane = tid & 63, wid = __builtin_amdgcn_readfirstlane(tid >> 6), wr = wid >> 1, wc = wid & 1;
;   const int m0 = mt * 128, n0 = nt * 256;
;   const int r = lane & 31, h = lane >> 5, key = (r >> 2) & 3;
;   constexpr int STG = 24576;
;   const int rowl = lane >> 2, cch = (lane & 3) ^ ((lane >> 4) & 3);
;   const unsigned voffA = (unsigned)(rowl * lda * 2 + cch * 16), voffB = (unsigned)(rowl * K * 2 + cch * 16);
;   const char* Abase = (const char*)(A + (size_t)m0 * lda) + (size_t)(wid * 2) * 32 * lda;
;   const char* Bbase = (const char*)(Bt + (size_t)n0 * K) + (size_t)(wid * 4) * 32 * K;
;   const size_t ablk = (size_t)32 * lda, bblk = (size_t)32 * K;
;   LAS char* lds = (LAS char*)smem;
;   LAS char* ldsA = lds + (wid * 2) * 1024;
;   LAS char* ldsB = lds + 8192 + (wid * 4) * 1024;
;     ...
;   const int x0 = ((0 + h) ^ key) * 16, x1 = ((2 + h) ^ key) * 16;
;   const int a_rd = (wr * 64 + r) * 64, b_rd = 8192 + (wc * 128 + r) * 64;
;   f32x16 acc[2][4];
; #pragma unroll
;   for (int i = 0; i < 2; ++i)
; #pragma unroll
;     for (int j = 0; j < 4; ++j)
; #pragma unroll
;       for (int e = 0; e < 16; ++e) acc[i][j][e] = 0.f;
;   const int nk = K >> 5;
;   DMA_STEP_(0, 0);
;   DMA_STEP_(1, STG);
;   asm volatile("s_waitcnt vmcnt(6)" ::: "memory");
;   __builtin_amdgcn_s_barrier();
	global_store_dwordx4 v[2:3], v[6:9], off
	v_mad_u64_u32 v[2:3], s[12:13], v0, s55, v[10:11]
	ds_read_b128 v[2:5], v2
	v_add_u32_e32 v6, s41, v0
	v_ashrrev_i32_e32 v7, 31, v6
	v_add_u32_e32 v0, 0x900, v189
	v_lshlrev_b64 v[6:7], 11, v[6:7]
	v_ashrrev_i32_e32 v0, 5, v0
	v_lshl_add_u64 v[14:15], v[12:13], 0, v[6:7]
	v_mad_u64_u32 v[6:7], s[12:13], v0, s55, v[10:11]
	ds_read_b128 v[6:9], v6
	s_waitcnt lgkmcnt(1)
	global_store_dwordx4 v[14:15], v[2:5], off
	s_nop 1
	v_add_u32_e32 v2, s41, v0
	v_ashrrev_i32_e32 v3, 31, v2
	v_lshlrev_b64 v[2:3], 11, v[2:3]
	v_add_u32_e32 v0, 0xa00, v189
	v_lshl_add_u64 v[2:3], v[12:13], 0, v[2:3]
	v_ashrrev_i32_e32 v0, 5, v0
	s_waitcnt lgkmcnt(0)
	global_store_dwordx4 v[2:3], v[6:9], off
	v_mad_u64_u32 v[2:3], s[12:13], v0, s55, v[10:11]
	ds_read_b128 v[2:5], v2
	v_add_u32_e32 v6, s41, v0
	v_ashrrev_i32_e32 v7, 31, v6
	v_add_u32_e32 v0, 0xb00, v189
	v_lshlrev_b64 v[6:7], 11, v[6:7]
	v_ashrrev_i32_e32 v0, 5, v0
	v_lshl_add_u64 v[14:15], v[12:13], 0, v[6:7]
	v_mad_u64_u32 v[6:7], s[12:13], v0, s55, v[10:11]
	ds_read_b128 v[6:9], v6
	s_waitcnt lgkmcnt(1)
	global_store_dwordx4 v[14:15], v[2:5], off
	s_nop 1
	v_add_u32_e32 v2, s41, v0
	v_ashrrev_i32_e32 v3, 31, v2
	v_lshlrev_b64 v[2:3], 11, v[2:3]
	v_add_u32_e32 v0, 0xc00, v189
	v_lshl_add_u64 v[2:3], v[12:13], 0, v[2:3]
	v_ashrrev_i32_e32 v0, 5, v0
	s_waitcnt lgkmcnt(0)
	global_store_dwordx4 v[2:3], v[6:9], off
	v_mad_u64_u32 v[2:3], s[12:13], v0, s55, v[10:11]
	ds_read_b128 v[2:5], v2
	v_add_u32_e32 v6, s41, v0
	v_ashrrev_i32_e32 v7, 31, v6
	v_add_u32_e32 v0, 0xd00, v189
	v_lshlrev_b64 v[6:7], 11, v[6:7]
	v_ashrrev_i32_e32 v0, 5, v0
	v_lshl_add_u64 v[14:15], v[12:13], 0, v[6:7]
	v_mad_u64_u32 v[6:7], s[12:13], v0, s55, v[10:11]
	ds_read_b128 v[6:9], v6
	s_waitcnt lgkmcnt(1)
	global_store_dwordx4 v[14:15], v[2:5], off
	s_nop 1
	v_add_u32_e32 v2, s41, v0
	v_ashrrev_i32_e32 v3, 31, v2
	v_lshlrev_b64 v[2:3], 11, v[2:3]
	v_add_u32_e32 v0, 0xe00, v189
	v_lshl_add_u64 v[2:3], v[12:13], 0, v[2:3]
	v_ashrrev_i32_e32 v0, 5, v0
	s_waitcnt lgkmcnt(0)
	global_store_dwordx4 v[2:3], v[6:9], off
	v_mad_u64_u32 v[2:3], s[12:13], v0, s55, v[10:11]
	ds_read_b128 v[2:5], v2
	v_add_u32_e32 v6, s41, v0
	v_ashrrev_i32_e32 v7, 31, v6
	v_add_u32_e32 v0, 0xf00, v189
	v_lshlrev_b64 v[6:7], 11, v[6:7]
	v_ashrrev_i32_e32 v0, 5, v0
	v_lshl_add_u64 v[14:15], v[12:13], 0, v[6:7]
	v_mad_u64_u32 v[6:7], s[12:13], v0, s55, v[10:11]
	ds_read_b128 v[6:9], v6
	s_waitcnt lgkmcnt(1)
	global_store_dwordx4 v[14:15], v[2:5], off
	s_mov_b64 s[12:13], 0
	s_nop 0
	v_add_u32_e32 v2, s41, v0
	v_ashrrev_i32_e32 v3, 31, v2
	v_lshlrev_b64 v[2:3], 11, v[2:3]
	v_lshl_add_u64 v[2:3], v[12:13], 0, v[2:3]
	s_waitcnt lgkmcnt(0)
	global_store_dwordx4 v[2:3], v[6:9], off
	s_barrier
.LBB0_150:
	s_and_b64 vcc, exec, s[12:13]
	s_cbranch_vccz .LBB0_145
	s_mul_hi_i32 s10, s40, 0x2aaaaaab
	s_lshr_b32 s11, s10, 31
	s_ashr_i32 s10, s10, 2
	s_add_i32 s10, s10, s11
	v_readlane_b32 s12, v252, 18
	v_mov_b32_e32 v189, v188
	s_mul_i32 s11, s10, 0xffffffe8
	s_lshl_b32 s10, s10, s12
	v_readlane_b32 s12, v252, 41
	s_add_i32 s10, s10, s12
	v_readfirstlane_b32 s43, v189
	s_ashr_i32 s45, s43, 6
	s_lshl_b32 s12, s40, 7
	s_add_i32 s11, s11, s40
	s_lshl_b32 s10, s10, 10
	s_and_b32 s12, s12, 0x380
	s_lshl_b32 s44, s45, 2
	s_ashr_i32 s43, s43, 1
	s_or_b32 s41, s10, s12
	s_lshl_b32 s10, s11, 5
	v_and_b32_e32 v0, 31, v189
	s_mov_b32 s59, 0
	s_lshl_b32 s44, s45, 12
	s_andn2_b32 s43, s43, 63
	s_and_b32 s12, s10, 0xffffff00
	s_add_i32 s44, s44, 16
	v_or_b32_e32 v197, s43, v0
	s_lshl_b32 s43, s45, 7
	s_lshl_b32 s10, s45, 1
	s_ashr_i32 s13, s12, 31
	s_add_i32 s60, s44, 0x2000
	s_and_b32 s43, s43, 0x80
	s_mul_i32 s57, s41, 0x1200
	s_mul_hi_i32 s56, s41, 0x1200
	s_add_u32 s57, s22, s57
	s_mul_i32 s11, s45, 0x24000
	s_addc_u32 s58, s23, s56
	s_mul_hi_i32 s10, s10, 0x12000
	s_add_u32 s56, s57, s11
	s_addc_u32 s57, s58, s10
	s_mul_i32 s11, s12, 64
	s_mov_b32 s10, 0
	s_add_u32 s11, s28, s11
	s_mul_i32 s47, s45, 0x1000
	s_addc_u32 s10, s29, s10
	v_bfe_u32 v2, v189, 2, 4
	v_lshlrev_b32_e32 v3, 4, v189
	s_add_u32 s58, s11, s47
	v_bitop3_b32 v5, v3, 48, v189 bitop3:0x48
	v_or_b32_e32 v3, s43, v0
	v_mul_u32_u24_e32 v0, 0x1200, v2
	s_addc_u32 s59, s10, s59
	s_lshl_b32 s10, s45, 11
	v_or_b32_e32 v0, v0, v5
	s_sub_i32 s45, s44, s10
	v_mul_u32_u24_e32 v6, 0x300, v2
	v_lshl_or_b32 v10, v2, 6, v5
	v_mov_b32_e32 v11, 0
	v_lshl_add_u64 v[192:193], s[56:57], 0, v[0:1]
	s_mov_b32 m0, s45
	s_mov_b64 s[10:11], 0x12000
	v_lshlrev_b32_e32 v218, 6, v3
	global_load_lds_dwordx4 v0, s[56:57]
	v_lshl_add_u64 v[2:3], v[192:193], 0, s[10:11]
	s_add_i32 m0, s45, 0x400
	v_or_b32_e32 v0, v6, v5
	global_load_lds_dwordx4 v[2:3], off
	v_lshl_add_u64 v[194:195], s[58:59], 0, v[10:11]
	s_mov_b32 m0, s60
	s_mov_b64 s[56:57], 0x3000
	global_load_lds_dwordx4 v[194:195], off
	global_load_lds_dwordx4 v[194:195], off offset:1024
	global_load_lds_dwordx4 v[194:195], off offset:2048
	global_load_lds_dwordx4 v[194:195], off offset:3072
	s_mov_b64 s[10:11], 0x6000
	s_mov_b64 s[56:57], 0x9000
	s_mov_b64 s[10:11], 0x12040
	s_add_i32 m0, s45, 0x6000
	v_lshl_add_u64 v[2:3], v[192:193], 0, 64
	global_load_lds_dwordx4 v[2:3], off
	v_lshl_add_u64 v[2:3], v[192:193], 0, s[10:11]
	s_add_i32 m0, s45, 0x6400
	s_mov_b64 s[56:57], 0x3040
	global_load_lds_dwordx4 v[2:3], off
	s_add_i32 m0, s44, 0x8000
	s_mov_b32 s100, 0xc000
	v_lshl_add_u64 v[2:3], v[194:195], 0, s[100:101]
	global_load_lds_dwordx4 v[2:3], off
	global_load_lds_dwordx4 v[2:3], off offset:1024
	global_load_lds_dwordx4 v[2:3], off offset:2048
	global_load_lds_dwordx4 v[2:3], off offset:3072
	s_mov_b64 s[10:11], 0x6040
	s_mov_b64 s[56:57], 0x9040
	v_bfe_u32 v196, v189, 5, 1
	v_bfe_u32 v5, v189, 2, 2
	v_lshrrev_b32_e32 v4, 2, v189
	s_lshl_b32 s100, s100, 1
	v_lshl_add_u64 v[194:195], v[194:195], 0, s[100:101]
	s_waitcnt vmcnt(6)
	s_barrier
; #define LAS __attribute__((address_space(3)))
; DI f32x16 mfma32(bf16x8 a, bf16x8 b, f32x16 c) { return __builtin_amdgcn_mfma_f32_32x32x16_bf16(a, b, c, 0, 0, 0); }
;     ...
;   f32x16 acc[2][4];
; #pragma unroll
;   for (int i = 0; i < 2; ++i)
; #pragma unroll
;     for (int j = 0; j < 4; ++j)
; #pragma unroll
;       for (int e = 0; e < 16; ++e) acc[i][j][e] = 0.f;
;   const int nk = K >> 5;
;   DMA_STEP_(0, 0);
;   DMA_STEP_(1, STG);
;   asm volatile("s_waitcnt vmcnt(6)" ::: "memory");
;   __builtin_amdgcn_s_barrier();
;   asm volatile("" ::: "memory");
;   int s0 = 0, s2 = 2 * STG;
;   for (int kt = 0; kt < nk; ++kt) {
;     const int kn = (kt + 2 < nk) ? (kt + 2) : (nk - 1);
;     const LAS char* cur = lds + s0;
;     bf16x8 af[2][2], bfr[2][4];
; #pragma unroll
;     for (int kk = 0; kk < 2; ++kk) {
;       const int xo = kk ? x1 : x0;
;       af[kk][0] = *(const LAS bf16x8*)(cur + a_rd + xo);
;       bfr[kk][0] = *(const LAS bf16x8*)(cur + b_rd + xo);
;       bfr[kk][1] = *(const LAS bf16x8*)(cur + b_rd + 2048 + xo);
;       af[kk][1] = *(const LAS bf16x8*)(cur + a_rd + 2048 + xo);
;       bfr[kk][2] = *(const LAS bf16x8*)(cur + b_rd + 4096 + xo);
;       bfr[kk][3] = *(const LAS bf16x8*)(cur + b_rd + 6144 + xo);
;     }
;     DMA_STEP_(kn, s2);
; #pragma unroll
;     for (int kk = 0; kk < 2; ++kk) {
;       acc[0][0] = mfma32(bfr[kk][0], af[kk][0], acc[0][0]); acc[0][1] = mfma32(bfr[kk][1], af[kk][0], acc[0][1]);
;       acc[1][0] = mfma32(bfr[kk][0], af[kk][1], acc[1][0]); acc[1][1] = mfma32(bfr[kk][1], af[kk][1], acc[1][1]);
;       acc[0][2] = mfma32(bfr[kk][2], af[kk][0], acc[0][2]); acc[0][3] = mfma32(bfr[kk][3], af[kk][0], acc[0][3]);
;       acc[1][2] = mfma32(bfr[kk][2], af[kk][1], acc[1][2]); acc[1][3] = mfma32(bfr[kk][3], af[kk][1], acc[1][3]);
;     }
;     __builtin_amdgcn_sched_group_barrier(0x100, 12, 0);
;     __builtin_amdgcn_sched_group_barrier(0x010, 6, 0);
;     __builtin_amdgcn_sched_group_barrier(0x008, 16, 0);
;     asm volatile("s_waitcnt vmcnt(6) lgkmcnt(0)" ::: "memory");
;     __builtin_amdgcn_s_barrier();
;     asm volatile("" ::: "memory");
;     s0 = (s0 == 2 * STG) ? 0 : s0 + STG;
;     s2 = (s2 == 2 * STG) ? 0 : s2 + STG;
	v_bitop3_b32 v2, v196, v5, 2 bitop3:0x36
	v_bitop3_b32 v0, v196, v4, 3 bitop3:0x78
	v_lshlrev_b32_e32 v220, 4, v2
	v_mov_b32_e32 v2, 0
	s_mov_b32 s42, 1
	s_mov_b32 s46, 0xc000
	v_lshlrev_b32_e32 v219, 6, v197
	v_lshlrev_b32_e32 v0, 4, v0
	s_mov_b32 s47, 0
	v_mov_b32_e32 v3, v2
	v_mov_b32_e32 v4, v2
	v_mov_b32_e32 v5, v2
	v_mov_b32_e32 v6, v2
	v_mov_b32_e32 v7, v2
	v_mov_b32_e32 v8, v2
	v_mov_b32_e32 v9, v2
	v_mov_b32_e32 v10, v2
	v_mov_b32_e32 v11, v2
	v_mov_b32_e32 v12, v2
	v_mov_b32_e32 v13, v2
	v_mov_b32_e32 v14, v2
	v_mov_b32_e32 v15, v2
	v_mov_b32_e32 v16, v2
	v_mov_b32_e32 v17, v2
	v_mov_b32_e32 v18, v2
	v_mov_b32_e32 v19, v2
	v_mov_b32_e32 v20, v2
	v_mov_b32_e32 v21, v2
	v_mov_b32_e32 v22, v2
	v_mov_b32_e32 v23, v2
	v_mov_b32_e32 v24, v2
	v_mov_b32_e32 v25, v2
	v_mov_b32_e32 v26, v2
	v_mov_b32_e32 v27, v2
	v_mov_b32_e32 v28, v2
	v_mov_b32_e32 v29, v2
	v_mov_b32_e32 v30, v2
	v_mov_b32_e32 v31, v2
	v_mov_b32_e32 v32, v2
	v_mov_b32_e32 v33, v2
	v_mov_b32_e32 v50, v2
	v_mov_b32_e32 v51, v2
	v_mov_b32_e32 v52, v2
	v_mov_b32_e32 v53, v2
	v_mov_b32_e32 v54, v2
	v_mov_b32_e32 v55, v2
	v_mov_b32_e32 v56, v2
	v_mov_b32_e32 v57, v2
	v_mov_b32_e32 v58, v2
	v_mov_b32_e32 v59, v2
	v_mov_b32_e32 v60, v2
	v_mov_b32_e32 v61, v2
	v_mov_b32_e32 v62, v2
	v_mov_b32_e32 v63, v2
	v_mov_b32_e32 v64, v2
	v_mov_b32_e32 v65, v2
	v_mov_b32_e32 v82, v2
	v_mov_b32_e32 v83, v2
	v_mov_b32_e32 v84, v2
	v_mov_b32_e32 v85, v2
	v_mov_b32_e32 v86, v2
	v_mov_b32_e32 v87, v2
	v_mov_b32_e32 v88, v2
	v_mov_b32_e32 v89, v2
	v_mov_b32_e32 v90, v2
	v_mov_b32_e32 v91, v2
	v_mov_b32_e32 v92, v2
	v_mov_b32_e32 v93, v2
	v_mov_b32_e32 v94, v2
	v_mov_b32_e32 v95, v2
	v_mov_b32_e32 v96, v2
	v_mov_b32_e32 v97, v2
	v_mov_b32_e32 v34, v2
	v_mov_b32_e32 v35, v2
	v_mov_b32_e32 v36, v2
	v_mov_b32_e32 v37, v2
	v_mov_b32_e32 v38, v2
	v_mov_b32_e32 v39, v2
	v_mov_b32_e32 v40, v2
	v_mov_b32_e32 v41, v2
	v_mov_b32_e32 v42, v2
	v_mov_b32_e32 v43, v2
	v_mov_b32_e32 v44, v2
	v_mov_b32_e32 v45, v2
	v_mov_b32_e32 v46, v2
	v_mov_b32_e32 v47, v2
	v_mov_b32_e32 v48, v2
	v_mov_b32_e32 v49, v2
	v_mov_b32_e32 v66, v2
	v_mov_b32_e32 v67, v2
	v_mov_b32_e32 v68, v2
	v_mov_b32_e32 v69, v2
	v_mov_b32_e32 v70, v2
	v_mov_b32_e32 v71, v2
	v_mov_b32_e32 v72, v2
	v_mov_b32_e32 v73, v2
	v_mov_b32_e32 v74, v2
	v_mov_b32_e32 v75, v2
	v_mov_b32_e32 v76, v2
	v_mov_b32_e32 v77, v2
	v_mov_b32_e32 v78, v2
	v_mov_b32_e32 v79, v2
	v_mov_b32_e32 v80, v2
	v_mov_b32_e32 v81, v2
	v_mov_b32_e32 v98, v2
	v_mov_b32_e32 v99, v2
	v_mov_b32_e32 v100, v2
	v_mov_b32_e32 v101, v2
	v_mov_b32_e32 v102, v2
	v_mov_b32_e32 v103, v2
	v_mov_b32_e32 v104, v2
	v_mov_b32_e32 v105, v2
	v_mov_b32_e32 v106, v2
	v_mov_b32_e32 v107, v2
	v_mov_b32_e32 v108, v2
	v_mov_b32_e32 v109, v2
	v_mov_b32_e32 v110, v2
	v_mov_b32_e32 v111, v2
	v_mov_b32_e32 v112, v2
	v_mov_b32_e32 v113, v2
	v_mov_b32_e32 v114, v2
	v_mov_b32_e32 v115, v2
	v_mov_b32_e32 v116, v2
	v_mov_b32_e32 v117, v2
	v_mov_b32_e32 v118, v2
	v_mov_b32_e32 v119, v2
	v_mov_b32_e32 v120, v2
	v_mov_b32_e32 v121, v2
	v_mov_b32_e32 v122, v2
	v_mov_b32_e32 v123, v2
	v_mov_b32_e32 v124, v2
	v_mov_b32_e32 v125, v2
	v_mov_b32_e32 v126, v2
	v_mov_b32_e32 v127, v2
	v_mov_b32_e32 v128, v2
	v_mov_b32_e32 v129, v2
	s_mov_b64 s[56:57], 0x3080
	s_mov_b64 s[58:59], 0x9080
	v_readfirstlane_b32 s10, v192
	v_readfirstlane_b32 s11, v193
	v_readfirstlane_b32 s100, v194
	v_readfirstlane_b32 s101, v195
	s_sub_u32 s10, s10, 0x100000
	s_subb_u32 s11, s11, 0
	s_sub_u32 s100, s100, 0x100000
	s_subb_u32 s101, s101, 0
	v_subrev_u32_e32 v238, s10, v192
	v_subrev_u32_e32 v239, s100, v194
	s_add_u32 vcc_lo, s10, s24
	s_addc_u32 vcc_hi, s11, s25
	s_add_u32 s70, s10, s36
	s_addc_u32 s71, s11, s37
	v_add3_u32 v226, v219, v0, 16
	v_add3_u32 v227, v218, v0, 16
	v_add3_u32 v228, v219, v220, 16
	v_add3_u32 v229, v218, v220, 16
	ds_read_b128 v[158:161], v226 offset:0
	ds_read_b128 v[182:185], v227 offset:8192
	ds_read_b128 v[178:181], v227 offset:10240
	ds_read_b128 v[162:165], v226 offset:2048
	ds_read_b128 v[174:177], v227 offset:12288
	ds_read_b128 v[170:173], v227 offset:14336
	s_setprio 1
.LBB0_152:
	ds_read_b128 v[138:141], v228 offset:0
	ds_read_b128 v[166:169], v229 offset:8192
	ds_read_b128 v[154:157], v229 offset:10240
	ds_read_b128 v[142:145], v228 offset:2048
	ds_read_b128 v[146:149], v229 offset:12288
	ds_read_b128 v[150:153], v229 offset:14336
	s_add_i32 m0, s45, 0xc000
	s_waitcnt lgkmcnt(6)
	v_mfma_f32_32x32x16_bf16 v[114:129], v[182:185], v[158:161], v[114:129]
	global_load_lds_dwordx4 v238, vcc
	s_add_i32 m0, s45, 0xc400
	s_add_u32 vcc_lo, vcc_lo, 64
	s_addc_u32 vcc_hi, vcc_hi, 0
	v_mfma_f32_32x32x16_bf16 v[98:113], v[178:181], v[158:161], v[98:113]
	global_load_lds_dwordx4 v238, s[70:71]
	s_add_i32 m0, s44, 0xe000
	s_add_u32 s70, s70, 64
	s_addc_u32 s71, s71, 0
	v_mfma_f32_32x32x16_bf16 v[66:81], v[182:185], v[162:165], v[66:81]
	global_load_lds_dwordx4 v239, s[100:101]
	v_mfma_f32_32x32x16_bf16 v[34:49], v[178:181], v[162:165], v[34:49]
	global_load_lds_dwordx4 v239, s[100:101] offset:1024
	v_mfma_f32_32x32x16_bf16 v[82:97], v[174:177], v[158:161], v[82:97]
	global_load_lds_dwordx4 v239, s[100:101] offset:2048
	v_mfma_f32_32x32x16_bf16 v[50:65], v[170:173], v[158:161], v[50:65]
	global_load_lds_dwordx4 v239, s[100:101] offset:3072
	s_add_u32 s100, s100, 0xc000
	s_addc_u32 s101, s101, 0
	v_mfma_f32_32x32x16_bf16 v[18:33], v[174:177], v[162:165], v[18:33]
	v_mfma_f32_32x32x16_bf16 v[2:17], v[170:173], v[162:165], v[2:17]
	s_waitcnt vmcnt(6) lgkmcnt(0)
	s_barrier
; #define LAS __attribute__((address_space(3)))
; DI f32x16 mfma32(bf16x8 a, bf16x8 b, f32x16 c) { return __builtin_amdgcn_mfma_f32_32x32x16_bf16(a, b, c, 0, 0, 0); }
;     ...
;   for (int kt = 0; kt < nk; ++kt) {
;     const int kn = (kt + 2 < nk) ? (kt + 2) : (nk - 1);
;     const LAS char* cur = lds + s0;
;     bf16x8 af[2][2], bfr[2][4];
; #pragma unroll
;     for (int kk = 0; kk < 2; ++kk) {
;       const int xo = kk ? x1 : x0;
;       af[kk][0] = *(const LAS bf16x8*)(cur + a_rd + xo);
;       bfr[kk][0] = *(const LAS bf16x8*)(cur + b_rd + xo);
;       bfr[kk][1] = *(const LAS bf16x8*)(cur + b_rd + 2048 + xo);
;       af[kk][1] = *(const LAS bf16x8*)(cur + a_rd + 2048 + xo);
;       bfr[kk][2] = *(const LAS bf16x8*)(cur + b_rd + 4096 + xo);
;       bfr[kk][3] = *(const LAS bf16x8*)(cur + b_rd + 6144 + xo);
;     }
;     DMA_STEP_(kn, s2);
; #pragma unroll
;     for (int kk = 0; kk < 2; ++kk) {
;       acc[0][0] = mfma32(bfr[kk][0], af[kk][0], acc[0][0]); acc[0][1] = mfma32(bfr[kk][1], af[kk][0], acc[0][1]);
;       acc[1][0] = mfma32(bfr[kk][0], af[kk][1], acc[1][0]); acc[1][1] = mfma32(bfr[kk][1], af[kk][1], acc[1][1]);
;       acc[0][2] = mfma32(bfr[kk][2], af[kk][0], acc[0][2]); acc[0][3] = mfma32(bfr[kk][3], af[kk][0], acc[0][3]);
;       acc[1][2] = mfma32(bfr[kk][2], af[kk][1], acc[1][2]); acc[1][3] = mfma32(bfr[kk][3], af[kk][1], acc[1][3]);
;     }
;     __builtin_amdgcn_sched_group_barrier(0x100, 12, 0);
;     __builtin_amdgcn_sched_group_barrier(0x010, 6, 0);
;     __builtin_amdgcn_sched_group_barrier(0x008, 16, 0);
;     asm volatile("s_waitcnt vmcnt(6) lgkmcnt(0)" ::: "memory");
;     __builtin_amdgcn_s_barrier();
;     asm volatile("" ::: "memory");
;     s0 = (s0 == 2 * STG) ? 0 : s0 + STG;
;     s2 = (s2 == 2 * STG) ? 0 : s2 + STG;
	ds_read_b128 v[158:161], v226 offset:24576
	ds_read_b128 v[182:185], v227 offset:32768
	ds_read_b128 v[178:181], v227 offset:34816
	ds_read_b128 v[162:165], v226 offset:26624
	ds_read_b128 v[174:177], v227 offset:36864
	ds_read_b128 v[170:173], v227 offset:38912
	v_mfma_f32_32x32x16_bf16 v[114:129], v[166:169], v[138:141], v[114:129]
	v_mfma_f32_32x32x16_bf16 v[98:113], v[154:157], v[138:141], v[98:113]
	v_mfma_f32_32x32x16_bf16 v[66:81], v[166:169], v[142:145], v[66:81]
	v_mfma_f32_32x32x16_bf16 v[34:49], v[154:157], v[142:145], v[34:49]
	v_mfma_f32_32x32x16_bf16 v[82:97], v[146:149], v[138:141], v[82:97]
	v_mfma_f32_32x32x16_bf16 v[50:65], v[150:153], v[138:141], v[50:65]
	v_mfma_f32_32x32x16_bf16 v[18:33], v[146:149], v[142:145], v[18:33]
	v_mfma_f32_32x32x16_bf16 v[2:17], v[150:153], v[142:145], v[2:17]
	ds_read_b128 v[138:141], v228 offset:24576
	ds_read_b128 v[166:169], v229 offset:32768
	ds_read_b128 v[154:157], v229 offset:34816
	ds_read_b128 v[142:145], v228 offset:26624
	ds_read_b128 v[146:149], v229 offset:36864
	ds_read_b128 v[150:153], v229 offset:38912
	s_add_i32 m0, s45, 0x0
	s_waitcnt lgkmcnt(6)
	v_mfma_f32_32x32x16_bf16 v[114:129], v[182:185], v[158:161], v[114:129]
	global_load_lds_dwordx4 v238, vcc
	s_add_i32 m0, s45, 0x400
	s_add_u32 vcc_lo, vcc_lo, 64
	s_addc_u32 vcc_hi, vcc_hi, 0
	v_mfma_f32_32x32x16_bf16 v[98:113], v[178:181], v[158:161], v[98:113]
	global_load_lds_dwordx4 v238, s[70:71]
	s_add_i32 m0, s44, 0x2000
	s_add_u32 s70, s70, 64
	s_addc_u32 s71, s71, 0
	v_mfma_f32_32x32x16_bf16 v[66:81], v[182:185], v[162:165], v[66:81]
	global_load_lds_dwordx4 v239, s[100:101]
	v_mfma_f32_32x32x16_bf16 v[34:49], v[178:181], v[162:165], v[34:49]
	global_load_lds_dwordx4 v239, s[100:101] offset:1024
	v_mfma_f32_32x32x16_bf16 v[82:97], v[174:177], v[158:161], v[82:97]
	global_load_lds_dwordx4 v239, s[100:101] offset:2048
	v_mfma_f32_32x32x16_bf16 v[50:65], v[170:173], v[158:161], v[50:65]
	global_load_lds_dwordx4 v239, s[100:101] offset:3072
	s_add_u32 s100, s100, 0xc000
	s_addc_u32 s101, s101, 0
	v_mfma_f32_32x32x16_bf16 v[18:33], v[174:177], v[162:165], v[18:33]
	v_mfma_f32_32x32x16_bf16 v[2:17], v[170:173], v[162:165], v[2:17]
	s_waitcnt vmcnt(6) lgkmcnt(0)
	s_barrier
	ds_read_b128 v[158:161], v226 offset:49152
	ds_read_b128 v[182:185], v227 offset:57344
	ds_read_b128 v[178:181], v227 offset:59392
	ds_read_b128 v[162:165], v226 offset:51200
	ds_read_b128 v[174:177], v227 offset:61440
	ds_read_b128 v[170:173], v227 offset:63488
	v_mfma_f32_32x32x16_bf16 v[114:129], v[166:169], v[138:141], v[114:129]
	v_mfma_f32_32x32x16_bf16 v[98:113], v[154:157], v[138:141], v[98:113]
	v_mfma_f32_32x32x16_bf16 v[66:81], v[166:169], v[142:145], v[66:81]
	v_mfma_f32_32x32x16_bf16 v[34:49], v[154:157], v[142:145], v[34:49]
	v_mfma_f32_32x32x16_bf16 v[82:97], v[146:149], v[138:141], v[82:97]
	v_mfma_f32_32x32x16_bf16 v[50:65], v[150:153], v[138:141], v[50:65]
	v_mfma_f32_32x32x16_bf16 v[18:33], v[146:149], v[142:145], v[18:33]
	v_mfma_f32_32x32x16_bf16 v[2:17], v[150:153], v[142:145], v[2:17]
	ds_read_b128 v[138:141], v228 offset:49152
	ds_read_b128 v[166:169], v229 offset:57344
	ds_read_b128 v[154:157], v229 offset:59392
	ds_read_b128 v[142:145], v228 offset:51200
	ds_read_b128 v[146:149], v229 offset:61440
	ds_read_b128 v[150:153], v229 offset:63488
	s_add_i32 m0, s45, 0x6000
	s_waitcnt lgkmcnt(6)
	v_mfma_f32_32x32x16_bf16 v[114:129], v[182:185], v[158:161], v[114:129]
	global_load_lds_dwordx4 v238, vcc
	s_add_i32 m0, s45, 0x6400
	s_add_u32 vcc_lo, vcc_lo, 64
	s_addc_u32 vcc_hi, vcc_hi, 0
	v_mfma_f32_32x32x16_bf16 v[98:113], v[178:181], v[158:161], v[98:113]
	global_load_lds_dwordx4 v238, s[70:71]
	s_add_i32 m0, s44, 0x8000
	s_add_u32 s70, s70, 64
	s_addc_u32 s71, s71, 0
	v_mfma_f32_32x32x16_bf16 v[66:81], v[182:185], v[162:165], v[66:81]
	global_load_lds_dwordx4 v239, s[100:101]
	v_mfma_f32_32x32x16_bf16 v[34:49], v[178:181], v[162:165], v[34:49]
	global_load_lds_dwordx4 v239, s[100:101] offset:1024
	v_mfma_f32_32x32x16_bf16 v[82:97], v[174:177], v[158:161], v[82:97]
	global_load_lds_dwordx4 v239, s[100:101] offset:2048
	v_mfma_f32_32x32x16_bf16 v[50:65], v[170:173], v[158:161], v[50:65]
	global_load_lds_dwordx4 v239, s[100:101] offset:3072
	s_add_u32 s100, s100, 0xc000
	s_addc_u32 s101, s101, 0
	v_mfma_f32_32x32x16_bf16 v[18:33], v[174:177], v[162:165], v[18:33]
	v_mfma_f32_32x32x16_bf16 v[2:17], v[170:173], v[162:165], v[2:17]
	s_waitcnt vmcnt(6) lgkmcnt(0)
	s_barrier
	ds_read_b128 v[158:161], v226 offset:0
	ds_read_b128 v[182:185], v227 offset:8192
	ds_read_b128 v[178:181], v227 offset:10240
	ds_read_b128 v[162:165], v226 offset:2048
	ds_read_b128 v[174:177], v227 offset:12288
	ds_read_b128 v[170:173], v227 offset:14336
	v_mfma_f32_32x32x16_bf16 v[114:129], v[166:169], v[138:141], v[114:129]
	v_mfma_f32_32x32x16_bf16 v[98:113], v[154:157], v[138:141], v[98:113]
	v_mfma_f32_32x32x16_bf16 v[66:81], v[166:169], v[142:145], v[66:81]
	v_mfma_f32_32x32x16_bf16 v[34:49], v[154:157], v[142:145], v[34:49]
	v_mfma_f32_32x32x16_bf16 v[82:97], v[146:149], v[138:141], v[82:97]
	v_mfma_f32_32x32x16_bf16 v[50:65], v[150:153], v[138:141], v[50:65]
	v_mfma_f32_32x32x16_bf16 v[18:33], v[146:149], v[142:145], v[18:33]
	v_mfma_f32_32x32x16_bf16 v[2:17], v[150:153], v[142:145], v[2:17]
	ds_read_b128 v[138:141], v228 offset:0
	ds_read_b128 v[166:169], v229 offset:8192
	ds_read_b128 v[154:157], v229 offset:10240
	ds_read_b128 v[142:145], v228 offset:2048
	ds_read_b128 v[146:149], v229 offset:12288
	ds_read_b128 v[150:153], v229 offset:14336
	s_add_i32 m0, s45, 0xc000
	s_waitcnt lgkmcnt(6)
	v_mfma_f32_32x32x16_bf16 v[114:129], v[182:185], v[158:161], v[114:129]
	global_load_lds_dwordx4 v238, vcc
	s_add_i32 m0, s45, 0xc400
	s_add_u32 vcc_lo, vcc_lo, 64
	s_addc_u32 vcc_hi, vcc_hi, 0
	v_mfma_f32_32x32x16_bf16 v[98:113], v[178:181], v[158:161], v[98:113]
	global_load_lds_dwordx4 v238, s[70:71]
	s_add_i32 m0, s44, 0xe000
	s_add_u32 s70, s70, 64
	s_addc_u32 s71, s71, 0
	v_mfma_f32_32x32x16_bf16 v[66:81], v[182:185], v[162:165], v[66:81]
	global_load_lds_dwordx4 v239, s[100:101]
	v_mfma_f32_32x32x16_bf16 v[34:49], v[178:181], v[162:165], v[34:49]
	global_load_lds_dwordx4 v239, s[100:101] offset:1024
	v_mfma_f32_32x32x16_bf16 v[82:97], v[174:177], v[158:161], v[82:97]
	global_load_lds_dwordx4 v239, s[100:101] offset:2048
	v_mfma_f32_32x32x16_bf16 v[50:65], v[170:173], v[158:161], v[50:65]
	global_load_lds_dwordx4 v239, s[100:101] offset:3072
	s_add_u32 s100, s100, 0xc000
	s_addc_u32 s101, s101, 0
	v_mfma_f32_32x32x16_bf16 v[18:33], v[174:177], v[162:165], v[18:33]
	v_mfma_f32_32x32x16_bf16 v[2:17], v[170:173], v[162:165], v[2:17]
	s_waitcnt vmcnt(6) lgkmcnt(0)
	s_barrier
; #define LAS __attribute__((address_space(3)))
; DI f32x16 mfma32(bf16x8 a, bf16x8 b, f32x16 c) { return __builtin_amdgcn_mfma_f32_32x32x16_bf16(a, b, c, 0, 0, 0); }
;     ...
;   for (int kt = 0; kt < nk; ++kt) {
;     const int kn = (kt + 2 < nk) ? (kt + 2) : (nk - 1);
;     const LAS char* cur = lds + s0;
;     bf16x8 af[2][2], bfr[2][4];
; #pragma unroll
;     for (int kk = 0; kk < 2; ++kk) {
;       const int xo = kk ? x1 : x0;
;       af[kk][0] = *(const LAS bf16x8*)(cur + a_rd + xo);
;       bfr[kk][0] = *(const LAS bf16x8*)(cur + b_rd + xo);
;       bfr[kk][1] = *(const LAS bf16x8*)(cur + b_rd + 2048 + xo);
;       af[kk][1] = *(const LAS bf16x8*)(cur + a_rd + 2048 + xo);
;       bfr[kk][2] = *(const LAS bf16x8*)(cur + b_rd + 4096 + xo);
;       bfr[kk][3] = *(const LAS bf16x8*)(cur + b_rd + 6144 + xo);
;     }
;     DMA_STEP_(kn, s2);
; #pragma unroll
;     for (int kk = 0; kk < 2; ++kk) {
;       acc[0][0] = mfma32(bfr[kk][0], af[kk][0], acc[0][0]); acc[0][1] = mfma32(bfr[kk][1], af[kk][0], acc[0][1]);
;       acc[1][0] = mfma32(bfr[kk][0], af[kk][1], acc[1][0]); acc[1][1] = mfma32(bfr[kk][1], af[kk][1], acc[1][1]);
;       acc[0][2] = mfma32(bfr[kk][2], af[kk][0], acc[0][2]); acc[0][3] = mfma32(bfr[kk][3], af[kk][0], acc[0][3]);
;       acc[1][2] = mfma32(bfr[kk][2], af[kk][1], acc[1][2]); acc[1][3] = mfma32(bfr[kk][3], af[kk][1], acc[1][3]);
;     }
;     __builtin_amdgcn_sched_group_barrier(0x100, 12, 0);
;     __builtin_amdgcn_sched_group_barrier(0x010, 6, 0);
;     __builtin_amdgcn_sched_group_barrier(0x008, 16, 0);
;     asm volatile("s_waitcnt vmcnt(6) lgkmcnt(0)" ::: "memory");
;     __builtin_amdgcn_s_barrier();
;     asm volatile("" ::: "memory");
;     s0 = (s0 == 2 * STG) ? 0 : s0 + STG;
;     s2 = (s2 == 2 * STG) ? 0 : s2 + STG;
	ds_read_b128 v[158:161], v226 offset:24576
	ds_read_b128 v[182:185], v227 offset:32768
	ds_read_b128 v[178:181], v227 offset:34816
	ds_read_b128 v[162:165], v226 offset:26624
	ds_read_b128 v[174:177], v227 offset:36864
	ds_read_b128 v[170:173], v227 offset:38912
	v_mfma_f32_32x32x16_bf16 v[114:129], v[166:169], v[138:141], v[114:129]
	v_mfma_f32_32x32x16_bf16 v[98:113], v[154:157], v[138:141], v[98:113]
	v_mfma_f32_32x32x16_bf16 v[66:81], v[166:169], v[142:145], v[66:81]
	v_mfma_f32_32x32x16_bf16 v[34:49], v[154:157], v[142:145], v[34:49]
	v_mfma_f32_32x32x16_bf16 v[82:97], v[146:149], v[138:141], v[82:97]
	v_mfma_f32_32x32x16_bf16 v[50:65], v[150:153], v[138:141], v[50:65]
	v_mfma_f32_32x32x16_bf16 v[18:33], v[146:149], v[142:145], v[18:33]
	v_mfma_f32_32x32x16_bf16 v[2:17], v[150:153], v[142:145], v[2:17]
	ds_read_b128 v[138:141], v228 offset:24576
	ds_read_b128 v[166:169], v229 offset:32768
	ds_read_b128 v[154:157], v229 offset:34816
	ds_read_b128 v[142:145], v228 offset:26624
	ds_read_b128 v[146:149], v229 offset:36864
	ds_read_b128 v[150:153], v229 offset:38912
	s_add_i32 m0, s45, 0x0
	s_waitcnt lgkmcnt(6)
	v_mfma_f32_32x32x16_bf16 v[114:129], v[182:185], v[158:161], v[114:129]
	global_load_lds_dwordx4 v238, vcc
	s_add_i32 m0, s45, 0x400
	s_add_u32 vcc_lo, vcc_lo, 64
	s_addc_u32 vcc_hi, vcc_hi, 0
	v_mfma_f32_32x32x16_bf16 v[98:113], v[178:181], v[158:161], v[98:113]
	global_load_lds_dwordx4 v238, s[70:71]
	s_add_i32 m0, s44, 0x2000
	s_add_u32 s70, s70, 64
	s_addc_u32 s71, s71, 0
	v_mfma_f32_32x32x16_bf16 v[66:81], v[182:185], v[162:165], v[66:81]
	global_load_lds_dwordx4 v239, s[100:101]
	v_mfma_f32_32x32x16_bf16 v[34:49], v[178:181], v[162:165], v[34:49]
	global_load_lds_dwordx4 v239, s[100:101] offset:1024
	v_mfma_f32_32x32x16_bf16 v[82:97], v[174:177], v[158:161], v[82:97]
	global_load_lds_dwordx4 v239, s[100:101] offset:2048
	v_mfma_f32_32x32x16_bf16 v[50:65], v[170:173], v[158:161], v[50:65]
	global_load_lds_dwordx4 v239, s[100:101] offset:3072
	s_add_u32 s100, s100, 0xc000
	s_addc_u32 s101, s101, 0
	v_mfma_f32_32x32x16_bf16 v[18:33], v[174:177], v[162:165], v[18:33]
	v_mfma_f32_32x32x16_bf16 v[2:17], v[170:173], v[162:165], v[2:17]
	s_waitcnt vmcnt(6) lgkmcnt(0)
	s_barrier
	ds_read_b128 v[158:161], v226 offset:49152
	ds_read_b128 v[182:185], v227 offset:57344
	ds_read_b128 v[178:181], v227 offset:59392
	ds_read_b128 v[162:165], v226 offset:51200
	ds_read_b128 v[174:177], v227 offset:61440
	ds_read_b128 v[170:173], v227 offset:63488
	v_mfma_f32_32x32x16_bf16 v[114:129], v[166:169], v[138:141], v[114:129]
	v_mfma_f32_32x32x16_bf16 v[98:113], v[154:157], v[138:141], v[98:113]
	v_mfma_f32_32x32x16_bf16 v[66:81], v[166:169], v[142:145], v[66:81]
	v_mfma_f32_32x32x16_bf16 v[34:49], v[154:157], v[142:145], v[34:49]
	v_mfma_f32_32x32x16_bf16 v[82:97], v[146:149], v[138:141], v[82:97]
	v_mfma_f32_32x32x16_bf16 v[50:65], v[150:153], v[138:141], v[50:65]
	v_mfma_f32_32x32x16_bf16 v[18:33], v[146:149], v[142:145], v[18:33]
	v_mfma_f32_32x32x16_bf16 v[2:17], v[150:153], v[142:145], v[2:17]
	ds_read_b128 v[138:141], v228 offset:49152
	ds_read_b128 v[166:169], v229 offset:57344
	ds_read_b128 v[154:157], v229 offset:59392
	ds_read_b128 v[142:145], v228 offset:51200
	ds_read_b128 v[146:149], v229 offset:61440
	ds_read_b128 v[150:153], v229 offset:63488
	s_add_i32 m0, s45, 0x6000
	s_waitcnt lgkmcnt(6)
	v_mfma_f32_32x32x16_bf16 v[114:129], v[182:185], v[158:161], v[114:129]
	global_load_lds_dwordx4 v238, vcc
	s_add_i32 m0, s45, 0x6400
	s_add_u32 vcc_lo, vcc_lo, 64
	s_addc_u32 vcc_hi, vcc_hi, 0
	v_mfma_f32_32x32x16_bf16 v[98:113], v[178:181], v[158:161], v[98:113]
	global_load_lds_dwordx4 v238, s[70:71]
	s_add_i32 m0, s44, 0x8000
	s_add_u32 s70, s70, 64
	s_addc_u32 s71, s71, 0
	v_mfma_f32_32x32x16_bf16 v[66:81], v[182:185], v[162:165], v[66:81]
	global_load_lds_dwordx4 v239, s[100:101]
	v_mfma_f32_32x32x16_bf16 v[34:49], v[178:181], v[162:165], v[34:49]
	global_load_lds_dwordx4 v239, s[100:101] offset:1024
	v_mfma_f32_32x32x16_bf16 v[82:97], v[174:177], v[158:161], v[82:97]
	global_load_lds_dwordx4 v239, s[100:101] offset:2048
	v_mfma_f32_32x32x16_bf16 v[50:65], v[170:173], v[158:161], v[50:65]
	global_load_lds_dwordx4 v239, s[100:101] offset:3072
	s_add_u32 s100, s100, 0xc000
	s_addc_u32 s101, s101, 0
	v_mfma_f32_32x32x16_bf16 v[18:33], v[174:177], v[162:165], v[18:33]
	v_mfma_f32_32x32x16_bf16 v[2:17], v[170:173], v[162:165], v[2:17]
	s_waitcnt vmcnt(6) lgkmcnt(0)
	s_barrier
	ds_read_b128 v[158:161], v226 offset:0
	ds_read_b128 v[182:185], v227 offset:8192
	ds_read_b128 v[178:181], v227 offset:10240
	ds_read_b128 v[162:165], v226 offset:2048
	ds_read_b128 v[174:177], v227 offset:12288
	ds_read_b128 v[170:173], v227 offset:14336
	v_mfma_f32_32x32x16_bf16 v[114:129], v[166:169], v[138:141], v[114:129]
	v_mfma_f32_32x32x16_bf16 v[98:113], v[154:157], v[138:141], v[98:113]
	v_mfma_f32_32x32x16_bf16 v[66:81], v[166:169], v[142:145], v[66:81]
	v_mfma_f32_32x32x16_bf16 v[34:49], v[154:157], v[142:145], v[34:49]
	v_mfma_f32_32x32x16_bf16 v[82:97], v[146:149], v[138:141], v[82:97]
	v_mfma_f32_32x32x16_bf16 v[50:65], v[150:153], v[138:141], v[50:65]
	v_mfma_f32_32x32x16_bf16 v[18:33], v[146:149], v[142:145], v[18:33]
	v_mfma_f32_32x32x16_bf16 v[2:17], v[150:153], v[142:145], v[2:17]
	s_add_i32 s42, s42, 6
	s_cmp_lg_u32 s42, 7
	s_cbranch_scc1 .LBB0_152
; #define LAS __attribute__((address_space(3)))
; DI f32x16 mfma32(bf16x8 a, bf16x8 b, f32x16 c) { return __builtin_amdgcn_mfma_f32_32x32x16_bf16(a, b, c, 0, 0, 0); }
;     ...
;   for (int kt = 0; kt < nk; ++kt) {
;     const int kn = (kt + 2 < nk) ? (kt + 2) : (nk - 1);
;     const LAS char* cur = lds + s0;
;     bf16x8 af[2][2], bfr[2][4];
; #pragma unroll
;     for (int kk = 0; kk < 2; ++kk) {
;       const int xo = kk ? x1 : x0;
;       af[kk][0] = *(const LAS bf16x8*)(cur + a_rd + xo);
;       bfr[kk][0] = *(const LAS bf16x8*)(cur + b_rd + xo);
;       bfr[kk][1] = *(const LAS bf16x8*)(cur + b_rd + 2048 + xo);
;       af[kk][1] = *(const LAS bf16x8*)(cur + a_rd + 2048 + xo);
;       bfr[kk][2] = *(const LAS bf16x8*)(cur + b_rd + 4096 + xo);
;       bfr[kk][3] = *(const LAS bf16x8*)(cur + b_rd + 6144 + xo);
;     }
;     DMA_STEP_(kn, s2);
; #pragma unroll
;     for (int kk = 0; kk < 2; ++kk) {
;       acc[0][0] = mfma32(bfr[kk][0], af[kk][0], acc[0][0]); acc[0][1] = mfma32(bfr[kk][1], af[kk][0], acc[0][1]);
;       acc[1][0] = mfma32(bfr[kk][0], af[kk][1], acc[1][0]); acc[1][1] = mfma32(bfr[kk][1], af[kk][1], acc[1][1]);
;       acc[0][2] = mfma32(bfr[kk][2], af[kk][0], acc[0][2]); acc[0][3] = mfma32(bfr[kk][3], af[kk][0], acc[0][3]);
;       acc[1][2] = mfma32(bfr[kk][2], af[kk][1], acc[1][2]); acc[1][3] = mfma32(bfr[kk][3], af[kk][1], acc[1][3]);
;     }
;     __builtin_amdgcn_sched_group_barrier(0x100, 12, 0);
;     __builtin_amdgcn_sched_group_barrier(0x010, 6, 0);
;     __builtin_amdgcn_sched_group_barrier(0x008, 16, 0);
;     asm volatile("s_waitcnt vmcnt(6) lgkmcnt(0)" ::: "memory");
;     __builtin_amdgcn_s_barrier();
;     asm volatile("" ::: "memory");
;     s0 = (s0 == 2 * STG) ? 0 : s0 + STG;
;     s2 = (s2 == 2 * STG) ? 0 : s2 + STG;
	ds_read_b128 v[138:141], v228 offset:0
	ds_read_b128 v[166:169], v229 offset:8192
	ds_read_b128 v[154:157], v229 offset:10240
	ds_read_b128 v[142:145], v228 offset:2048
	ds_read_b128 v[146:149], v229 offset:12288
	ds_read_b128 v[150:153], v229 offset:14336
	s_add_i32 m0, s45, 0xc000
	s_waitcnt lgkmcnt(6)
	v_mfma_f32_32x32x16_bf16 v[114:129], v[182:185], v[158:161], v[114:129]
	global_load_lds_dwordx4 v238, vcc
	s_add_i32 m0, s45, 0xc400
	s_add_u32 vcc_lo, vcc_lo, 64
	s_addc_u32 vcc_hi, vcc_hi, 0
	v_mfma_f32_32x32x16_bf16 v[98:113], v[178:181], v[158:161], v[98:113]
	global_load_lds_dwordx4 v238, s[70:71]
	s_add_i32 m0, s44, 0xe000
	s_add_u32 s70, s70, 64
	s_addc_u32 s71, s71, 0
	v_mfma_f32_32x32x16_bf16 v[66:81], v[182:185], v[162:165], v[66:81]
	global_load_lds_dwordx4 v239, s[100:101]
	v_mfma_f32_32x32x16_bf16 v[34:49], v[178:181], v[162:165], v[34:49]
	global_load_lds_dwordx4 v239, s[100:101] offset:1024
	v_mfma_f32_32x32x16_bf16 v[82:97], v[174:177], v[158:161], v[82:97]
	global_load_lds_dwordx4 v239, s[100:101] offset:2048
	v_mfma_f32_32x32x16_bf16 v[50:65], v[170:173], v[158:161], v[50:65]
	global_load_lds_dwordx4 v239, s[100:101] offset:3072
	s_add_u32 s100, s100, 0xc000
	s_addc_u32 s101, s101, 0
	v_mfma_f32_32x32x16_bf16 v[18:33], v[174:177], v[162:165], v[18:33]
	v_mfma_f32_32x32x16_bf16 v[2:17], v[170:173], v[162:165], v[2:17]
	s_waitcnt vmcnt(6) lgkmcnt(0)
	s_barrier
	ds_read_b128 v[158:161], v226 offset:24576
	ds_read_b128 v[182:185], v227 offset:32768
	ds_read_b128 v[178:181], v227 offset:34816
	ds_read_b128 v[162:165], v226 offset:26624
	ds_read_b128 v[174:177], v227 offset:36864
	ds_read_b128 v[170:173], v227 offset:38912
	v_mfma_f32_32x32x16_bf16 v[114:129], v[166:169], v[138:141], v[114:129]
	v_mfma_f32_32x32x16_bf16 v[98:113], v[154:157], v[138:141], v[98:113]
	v_mfma_f32_32x32x16_bf16 v[66:81], v[166:169], v[142:145], v[66:81]
	v_mfma_f32_32x32x16_bf16 v[34:49], v[154:157], v[142:145], v[34:49]
	v_mfma_f32_32x32x16_bf16 v[82:97], v[146:149], v[138:141], v[82:97]
	v_mfma_f32_32x32x16_bf16 v[50:65], v[150:153], v[138:141], v[50:65]
	v_mfma_f32_32x32x16_bf16 v[18:33], v[146:149], v[142:145], v[18:33]
	v_mfma_f32_32x32x16_bf16 v[2:17], v[150:153], v[142:145], v[2:17]
	ds_read_b128 v[138:141], v228 offset:24576
	ds_read_b128 v[166:169], v229 offset:32768
	ds_read_b128 v[154:157], v229 offset:34816
	ds_read_b128 v[142:145], v228 offset:26624
	ds_read_b128 v[146:149], v229 offset:36864
	ds_read_b128 v[150:153], v229 offset:38912
	s_add_i32 m0, s45, 0x0
	s_waitcnt lgkmcnt(6)
	v_mfma_f32_32x32x16_bf16 v[114:129], v[182:185], v[158:161], v[114:129]
	global_load_lds_dwordx4 v238, vcc
	s_add_i32 m0, s45, 0x400
	s_add_u32 vcc_lo, vcc_lo, 64
	s_addc_u32 vcc_hi, vcc_hi, 0
	v_mfma_f32_32x32x16_bf16 v[98:113], v[178:181], v[158:161], v[98:113]
	global_load_lds_dwordx4 v238, s[70:71]
	s_add_i32 m0, s44, 0x2000
	s_add_u32 s70, s70, 64
	s_addc_u32 s71, s71, 0
	v_mfma_f32_32x32x16_bf16 v[66:81], v[182:185], v[162:165], v[66:81]
	global_load_lds_dwordx4 v239, s[100:101]
	v_mfma_f32_32x32x16_bf16 v[34:49], v[178:181], v[162:165], v[34:49]
	global_load_lds_dwordx4 v239, s[100:101] offset:1024
	v_mfma_f32_32x32x16_bf16 v[82:97], v[174:177], v[158:161], v[82:97]
	global_load_lds_dwordx4 v239, s[100:101] offset:2048
	v_mfma_f32_32x32x16_bf16 v[50:65], v[170:173], v[158:161], v[50:65]
	global_load_lds_dwordx4 v239, s[100:101] offset:3072
	s_add_u32 s100, s100, 0xc000
	s_addc_u32 s101, s101, 0
	v_mfma_f32_32x32x16_bf16 v[18:33], v[174:177], v[162:165], v[18:33]
	v_mfma_f32_32x32x16_bf16 v[2:17], v[170:173], v[162:165], v[2:17]
	s_waitcnt vmcnt(6) lgkmcnt(0)
	s_barrier
	ds_read_b128 v[158:161], v226 offset:49152
	ds_read_b128 v[182:185], v227 offset:57344
	ds_read_b128 v[178:181], v227 offset:59392
	ds_read_b128 v[162:165], v226 offset:51200
	ds_read_b128 v[174:177], v227 offset:61440
	ds_read_b128 v[170:173], v227 offset:63488
	v_mfma_f32_32x32x16_bf16 v[114:129], v[166:169], v[138:141], v[114:129]
	v_mfma_f32_32x32x16_bf16 v[98:113], v[154:157], v[138:141], v[98:113]
	v_mfma_f32_32x32x16_bf16 v[66:81], v[166:169], v[142:145], v[66:81]
	v_mfma_f32_32x32x16_bf16 v[34:49], v[154:157], v[142:145], v[34:49]
	v_mfma_f32_32x32x16_bf16 v[82:97], v[146:149], v[138:141], v[82:97]
	v_mfma_f32_32x32x16_bf16 v[50:65], v[150:153], v[138:141], v[50:65]
	v_mfma_f32_32x32x16_bf16 v[18:33], v[146:149], v[142:145], v[18:33]
	v_mfma_f32_32x32x16_bf16 v[2:17], v[150:153], v[142:145], v[2:17]
	ds_read_b128 v[138:141], v228 offset:49152
	ds_read_b128 v[166:169], v229 offset:57344
	ds_read_b128 v[154:157], v229 offset:59392
	ds_read_b128 v[142:145], v228 offset:51200
	ds_read_b128 v[146:149], v229 offset:61440
	ds_read_b128 v[150:153], v229 offset:63488
	s_add_i32 m0, s45, 0x6000
	s_waitcnt lgkmcnt(6)
	v_mfma_f32_32x32x16_bf16 v[114:129], v[182:185], v[158:161], v[114:129]
	global_load_lds_dwordx4 v238, vcc
	s_add_i32 m0, s45, 0x6400
	s_add_u32 vcc_lo, vcc_lo, 64
	s_addc_u32 vcc_hi, vcc_hi, 0
	v_mfma_f32_32x32x16_bf16 v[98:113], v[178:181], v[158:161], v[98:113]
	global_load_lds_dwordx4 v238, s[70:71]
	s_add_i32 m0, s44, 0x8000
	s_add_u32 s70, s70, 64
	s_addc_u32 s71, s71, 0
	v_mfma_f32_32x32x16_bf16 v[66:81], v[182:185], v[162:165], v[66:81]
	global_load_lds_dwordx4 v239, s[100:101]
	v_mfma_f32_32x32x16_bf16 v[34:49], v[178:181], v[162:165], v[34:49]
	global_load_lds_dwordx4 v239, s[100:101] offset:1024
	v_mfma_f32_32x32x16_bf16 v[82:97], v[174:177], v[158:161], v[82:97]
	global_load_lds_dwordx4 v239, s[100:101] offset:2048
	v_mfma_f32_32x32x16_bf16 v[50:65], v[170:173], v[158:161], v[50:65]
	global_load_lds_dwordx4 v239, s[100:101] offset:3072
	s_add_u32 s100, s100, 0xc000
	s_addc_u32 s101, s101, 0
	v_mfma_f32_32x32x16_bf16 v[18:33], v[174:177], v[162:165], v[18:33]
	v_mfma_f32_32x32x16_bf16 v[2:17], v[170:173], v[162:165], v[2:17]
	s_waitcnt vmcnt(6) lgkmcnt(0)
	s_barrier
; #define LAS __attribute__((address_space(3)))
; DI unsigned pk2(float a, float b) { f32x2 v = {a, b}; bf2_t r = __builtin_convertvector(v, bf2_t); return __builtin_bit_cast(unsigned, r); }
;     ...
;   for (int kt = 0; kt < nk; ++kt) {
;     const int kn = (kt + 2 < nk) ? (kt + 2) : (nk - 1);
;     const LAS char* cur = lds + s0;
;     bf16x8 af[2][2], bfr[2][4];
; #pragma unroll
;     for (int kk = 0; kk < 2; ++kk) {
;       const int xo = kk ? x1 : x0;
;       af[kk][0] = *(const LAS bf16x8*)(cur + a_rd + xo);
;       bfr[kk][0] = *(const LAS bf16x8*)(cur + b_rd + xo);
;       bfr[kk][1] = *(const LAS bf16x8*)(cur + b_rd + 2048 + xo);
;       af[kk][1] = *(const LAS bf16x8*)(cur + a_rd + 2048 + xo);
;       bfr[kk][2] = *(const LAS bf16x8*)(cur + b_rd + 4096 + xo);
;       bfr[kk][3] = *(const LAS bf16x8*)(cur + b_rd + 6144 + xo);
;     }
;     DMA_STEP_(kn, s2);
; #pragma unroll
;     for (int kk = 0; kk < 2; ++kk) {
;       acc[0][0] = mfma32(bfr[kk][0], af[kk][0], acc[0][0]); acc[0][1] = mfma32(bfr[kk][1], af[kk][0], acc[0][1]);
;       acc[1][0] = mfma32(bfr[kk][0], af[kk][1], acc[1][0]); acc[1][1] = mfma32(bfr[kk][1], af[kk][1], acc[1][1]);
;       acc[0][2] = mfma32(bfr[kk][2], af[kk][0], acc[0][2]); acc[0][3] = mfma32(bfr[kk][3], af[kk][0], acc[0][3]);
;       acc[1][2] = mfma32(bfr[kk][2], af[kk][1], acc[1][2]); acc[1][3] = mfma32(bfr[kk][3], af[kk][1], acc[1][3]);
;     }
;     __builtin_amdgcn_sched_group_barrier(0x100, 12, 0);
;     __builtin_amdgcn_sched_group_barrier(0x010, 6, 0);
;     __builtin_amdgcn_sched_group_barrier(0x008, 16, 0);
;     asm volatile("s_waitcnt vmcnt(6) lgkmcnt(0)" ::: "memory");
;     __builtin_amdgcn_s_barrier();
;     asm volatile("" ::: "memory");
;     s0 = (s0 == 2 * STG) ? 0 : s0 + STG;
;     s2 = (s2 == 2 * STG) ? 0 : s2 + STG;
;   }
;   asm volatile("s_waitcnt vmcnt(0)" ::: "memory");
;   __builtin_amdgcn_s_barrier();
;   asm volatile("" ::: "memory");
;     ...
;   {
;     const int h = lane >> 5, cl = lane & 31;
; #pragma unroll
;     for (int i = 0; i < 2; ++i)
; #pragma unroll
;       for (int j = 0; j < 4; ++j)
; #pragma unroll
;         for (int g = 0; g < 4; ++g) {
;           u32x2 w; w.x = pk2(acc[i][j][4 * g], acc[i][j][4 * g + 1]); w.y = pk2(acc[i][j][4 * g + 2], acc[i][j][4 * g + 3]);
;           *(u32x2*)(smem + (wr * 64 + i * 32 + cl) * 528 + (wc * 128 + j * 32 + 8 * g + 4 * h) * 2) = w;
	ds_read_b128 v[158:161], v226 offset:0
	ds_read_b128 v[182:185], v227 offset:8192
	ds_read_b128 v[178:181], v227 offset:10240
	ds_read_b128 v[162:165], v226 offset:2048
	ds_read_b128 v[174:177], v227 offset:12288
	ds_read_b128 v[170:173], v227 offset:14336
	v_mfma_f32_32x32x16_bf16 v[114:129], v[166:169], v[138:141], v[114:129]
	v_mfma_f32_32x32x16_bf16 v[98:113], v[154:157], v[138:141], v[98:113]
	v_mfma_f32_32x32x16_bf16 v[66:81], v[166:169], v[142:145], v[66:81]
	v_mfma_f32_32x32x16_bf16 v[34:49], v[154:157], v[142:145], v[34:49]
	v_mfma_f32_32x32x16_bf16 v[82:97], v[146:149], v[138:141], v[82:97]
	v_mfma_f32_32x32x16_bf16 v[50:65], v[150:153], v[138:141], v[50:65]
	v_mfma_f32_32x32x16_bf16 v[18:33], v[146:149], v[142:145], v[18:33]
	v_mfma_f32_32x32x16_bf16 v[2:17], v[150:153], v[142:145], v[2:17]
	ds_read_b128 v[138:141], v228 offset:0
	ds_read_b128 v[166:169], v229 offset:8192
	ds_read_b128 v[154:157], v229 offset:10240
	ds_read_b128 v[142:145], v228 offset:2048
	ds_read_b128 v[146:149], v229 offset:12288
	ds_read_b128 v[150:153], v229 offset:14336
	s_add_i32 m0, s45, 0xc000
	s_waitcnt lgkmcnt(6)
	v_mfma_f32_32x32x16_bf16 v[114:129], v[182:185], v[158:161], v[114:129]
	global_load_lds_dwordx4 v238, vcc
	s_add_i32 m0, s45, 0xc400
	s_add_u32 vcc_lo, vcc_lo, 64
	s_addc_u32 vcc_hi, vcc_hi, 0
	v_mfma_f32_32x32x16_bf16 v[98:113], v[178:181], v[158:161], v[98:113]
	global_load_lds_dwordx4 v238, s[70:71]
	s_add_i32 m0, s44, 0xe000
	s_add_u32 s70, s70, 64
	s_addc_u32 s71, s71, 0
	v_mfma_f32_32x32x16_bf16 v[66:81], v[182:185], v[162:165], v[66:81]
	global_load_lds_dwordx4 v239, s[100:101]
	v_mfma_f32_32x32x16_bf16 v[34:49], v[178:181], v[162:165], v[34:49]
	global_load_lds_dwordx4 v239, s[100:101] offset:1024
	v_mfma_f32_32x32x16_bf16 v[82:97], v[174:177], v[158:161], v[82:97]
	global_load_lds_dwordx4 v239, s[100:101] offset:2048
	v_mfma_f32_32x32x16_bf16 v[50:65], v[170:173], v[158:161], v[50:65]
	global_load_lds_dwordx4 v239, s[100:101] offset:3072
	s_add_u32 s100, s100, 0xc000
	s_addc_u32 s101, s101, 0
	v_mfma_f32_32x32x16_bf16 v[18:33], v[174:177], v[162:165], v[18:33]
	v_mfma_f32_32x32x16_bf16 v[2:17], v[170:173], v[162:165], v[2:17]
	s_waitcnt vmcnt(6) lgkmcnt(0)
	s_barrier
	ds_read_b128 v[158:161], v226 offset:24576
	ds_read_b128 v[182:185], v227 offset:32768
	ds_read_b128 v[178:181], v227 offset:34816
	ds_read_b128 v[162:165], v226 offset:26624
	ds_read_b128 v[174:177], v227 offset:36864
	ds_read_b128 v[170:173], v227 offset:38912
	v_mfma_f32_32x32x16_bf16 v[114:129], v[166:169], v[138:141], v[114:129]
	v_mfma_f32_32x32x16_bf16 v[98:113], v[154:157], v[138:141], v[98:113]
	v_mfma_f32_32x32x16_bf16 v[66:81], v[166:169], v[142:145], v[66:81]
	v_mfma_f32_32x32x16_bf16 v[34:49], v[154:157], v[142:145], v[34:49]
	v_mfma_f32_32x32x16_bf16 v[82:97], v[146:149], v[138:141], v[82:97]
	v_mfma_f32_32x32x16_bf16 v[50:65], v[150:153], v[138:141], v[50:65]
	v_mfma_f32_32x32x16_bf16 v[18:33], v[146:149], v[142:145], v[18:33]
	v_mfma_f32_32x32x16_bf16 v[2:17], v[150:153], v[142:145], v[2:17]
	ds_read_b128 v[138:141], v228 offset:24576
	ds_read_b128 v[166:169], v229 offset:32768
	ds_read_b128 v[154:157], v229 offset:34816
	ds_read_b128 v[142:145], v228 offset:26624
	ds_read_b128 v[146:149], v229 offset:36864
	ds_read_b128 v[150:153], v229 offset:38912
	s_waitcnt lgkmcnt(6)
	v_mfma_f32_32x32x16_bf16 v[114:129], v[182:185], v[158:161], v[114:129]
	v_mfma_f32_32x32x16_bf16 v[98:113], v[178:181], v[158:161], v[98:113]
	v_mfma_f32_32x32x16_bf16 v[66:81], v[182:185], v[162:165], v[66:81]
	v_mfma_f32_32x32x16_bf16 v[34:49], v[178:181], v[162:165], v[34:49]
	v_mfma_f32_32x32x16_bf16 v[82:97], v[174:177], v[158:161], v[82:97]
	v_mfma_f32_32x32x16_bf16 v[50:65], v[170:173], v[158:161], v[50:65]
	v_mfma_f32_32x32x16_bf16 v[18:33], v[174:177], v[162:165], v[18:33]
	v_mfma_f32_32x32x16_bf16 v[2:17], v[170:173], v[162:165], v[2:17]
	s_waitcnt vmcnt(0) lgkmcnt(0)
	s_barrier
	ds_read_b128 v[158:161], v226 offset:49152
	ds_read_b128 v[182:185], v227 offset:57344
	ds_read_b128 v[178:181], v227 offset:59392
	ds_read_b128 v[162:165], v226 offset:51200
	ds_read_b128 v[174:177], v227 offset:61440
	ds_read_b128 v[170:173], v227 offset:63488
	v_mfma_f32_32x32x16_bf16 v[114:129], v[166:169], v[138:141], v[114:129]
	v_mfma_f32_32x32x16_bf16 v[98:113], v[154:157], v[138:141], v[98:113]
	v_mfma_f32_32x32x16_bf16 v[66:81], v[166:169], v[142:145], v[66:81]
	v_mfma_f32_32x32x16_bf16 v[34:49], v[154:157], v[142:145], v[34:49]
	v_mfma_f32_32x32x16_bf16 v[82:97], v[146:149], v[138:141], v[82:97]
	v_mfma_f32_32x32x16_bf16 v[50:65], v[150:153], v[138:141], v[50:65]
	v_mfma_f32_32x32x16_bf16 v[18:33], v[146:149], v[142:145], v[18:33]
	v_mfma_f32_32x32x16_bf16 v[2:17], v[150:153], v[142:145], v[2:17]
	ds_read_b128 v[138:141], v228 offset:49152
	ds_read_b128 v[166:169], v229 offset:57344
	ds_read_b128 v[154:157], v229 offset:59392
	ds_read_b128 v[142:145], v228 offset:51200
	ds_read_b128 v[146:149], v229 offset:61440
	ds_read_b128 v[150:153], v229 offset:63488
	s_waitcnt lgkmcnt(6)
	v_mfma_f32_32x32x16_bf16 v[114:129], v[182:185], v[158:161], v[114:129]
	v_mfma_f32_32x32x16_bf16 v[98:113], v[178:181], v[158:161], v[98:113]
	v_mfma_f32_32x32x16_bf16 v[66:81], v[182:185], v[162:165], v[66:81]
	v_mfma_f32_32x32x16_bf16 v[34:49], v[178:181], v[162:165], v[34:49]
	v_mfma_f32_32x32x16_bf16 v[82:97], v[174:177], v[158:161], v[82:97]
	v_mfma_f32_32x32x16_bf16 v[50:65], v[170:173], v[158:161], v[50:65]
	v_mfma_f32_32x32x16_bf16 v[18:33], v[174:177], v[162:165], v[18:33]
	v_mfma_f32_32x32x16_bf16 v[2:17], v[170:173], v[162:165], v[2:17]
	s_waitcnt lgkmcnt(0)
	v_mfma_f32_32x32x16_bf16 v[114:129], v[166:169], v[138:141], v[114:129]
	v_mfma_f32_32x32x16_bf16 v[98:113], v[154:157], v[138:141], v[98:113]
	v_mfma_f32_32x32x16_bf16 v[66:81], v[166:169], v[142:145], v[66:81]
	v_mfma_f32_32x32x16_bf16 v[34:49], v[154:157], v[142:145], v[34:49]
	v_mfma_f32_32x32x16_bf16 v[82:97], v[146:149], v[138:141], v[82:97]
	v_mfma_f32_32x32x16_bf16 v[50:65], v[150:153], v[138:141], v[50:65]
	v_mfma_f32_32x32x16_bf16 v[18:33], v[146:149], v[142:145], v[18:33]
	v_mfma_f32_32x32x16_bf16 v[2:17], v[150:153], v[142:145], v[2:17]
	s_waitcnt lgkmcnt(0)
	s_mov_b32 s101, 0
	s_mov_b32 s71, 0
	s_setprio 0
	v_mul_lo_u32 v0, v197, s55
	v_add_u32_e32 v0, 16, v0
	s_nop 1
	v_cvt_pk_bf16_f32 v114, v114, v115
	v_cvt_pk_bf16_f32 v115, v116, v117
	v_lshlrev_b32_e32 v116, 3, v196
	s_lshl_b32 s10, s43, 1
	v_add3_u32 v0, v0, v116, s10
	v_cvt_pk_bf16_f32 v116, v118, v119
	v_cvt_pk_bf16_f32 v117, v120, v121
	v_cvt_pk_bf16_f32 v98, v98, v99
	v_cvt_pk_bf16_f32 v99, v100, v101
	v_cvt_pk_bf16_f32 v100, v102, v103
	v_cvt_pk_bf16_f32 v101, v104, v105
	v_cvt_pk_bf16_f32 v82, v82, v83
	v_cvt_pk_bf16_f32 v83, v84, v85
	v_cvt_pk_bf16_f32 v84, v86, v87
	v_cvt_pk_bf16_f32 v85, v88, v89
	v_cvt_pk_bf16_f32 v50, v50, v51
	v_cvt_pk_bf16_f32 v51, v52, v53
	v_cvt_pk_bf16_f32 v52, v54, v55
	v_cvt_pk_bf16_f32 v53, v56, v57
	s_waitcnt vmcnt(0)
	s_barrier
; DI unsigned pk2(float a, float b) { f32x2 v = {a, b}; bf2_t r = __builtin_convertvector(v, bf2_t); return __builtin_bit_cast(unsigned, r); }
;     ...
;   {
;     const int h = lane >> 5, cl = lane & 31;
; #pragma unroll
;     for (int i = 0; i < 2; ++i)
; #pragma unroll
;       for (int j = 0; j < 4; ++j)
; #pragma unroll
;         for (int g = 0; g < 4; ++g) {
;           u32x2 w; w.x = pk2(acc[i][j][4 * g], acc[i][j][4 * g + 1]); w.y = pk2(acc[i][j][4 * g + 2], acc[i][j][4 * g + 3]);
;           *(u32x2*)(smem + (wr * 64 + i * 32 + cl) * 528 + (wc * 128 + j * 32 + 8 * g + 4 * h) * 2) = w;
;         }
;   }
;   __syncthreads();
	ds_write2_b64 v0, v[114:115], v[116:117] offset1:2
	v_cvt_pk_bf16_f32 v114, v122, v123
	v_cvt_pk_bf16_f32 v115, v124, v125
	v_cvt_pk_bf16_f32 v116, v126, v127
	v_cvt_pk_bf16_f32 v117, v128, v129
	ds_write2_b64 v0, v[98:99], v[100:101] offset0:8 offset1:10
	v_cvt_pk_bf16_f32 v98, v106, v107
	v_cvt_pk_bf16_f32 v99, v108, v109
	v_cvt_pk_bf16_f32 v100, v110, v111
	v_cvt_pk_bf16_f32 v101, v112, v113
	ds_write2_b64 v0, v[82:83], v[84:85] offset0:16 offset1:18
	v_cvt_pk_bf16_f32 v82, v90, v91
	v_cvt_pk_bf16_f32 v83, v92, v93
	v_cvt_pk_bf16_f32 v84, v94, v95
	v_cvt_pk_bf16_f32 v85, v96, v97
	ds_write2_b64 v0, v[50:51], v[52:53] offset0:24 offset1:26
	v_cvt_pk_bf16_f32 v50, v58, v59
	v_cvt_pk_bf16_f32 v51, v60, v61
	v_cvt_pk_bf16_f32 v52, v62, v63
	v_cvt_pk_bf16_f32 v53, v64, v65
	ds_write2_b64 v0, v[114:115], v[116:117] offset0:4 offset1:6
	ds_write2_b64 v0, v[98:99], v[100:101] offset0:12 offset1:14
	ds_write2_b64 v0, v[82:83], v[84:85] offset0:20 offset1:22
	ds_write2_b64 v0, v[50:51], v[52:53] offset0:28 offset1:30
	v_cvt_pk_bf16_f32 v50, v66, v67
	v_cvt_pk_bf16_f32 v51, v68, v69
	v_cvt_pk_bf16_f32 v52, v70, v71
	v_cvt_pk_bf16_f32 v53, v72, v73
	v_add_u32_e32 v0, 0x4000, v0
	v_cvt_pk_bf16_f32 v34, v34, v35
	v_cvt_pk_bf16_f32 v35, v36, v37
	v_cvt_pk_bf16_f32 v36, v38, v39
	v_cvt_pk_bf16_f32 v37, v40, v41
	v_cvt_pk_bf16_f32 v18, v18, v19
	v_cvt_pk_bf16_f32 v19, v20, v21
	v_cvt_pk_bf16_f32 v20, v22, v23
	v_cvt_pk_bf16_f32 v21, v24, v25
	v_cvt_pk_bf16_f32 v2, v2, v3
	v_cvt_pk_bf16_f32 v3, v4, v5
	v_cvt_pk_bf16_f32 v4, v6, v7
	v_cvt_pk_bf16_f32 v5, v8, v9
	ds_write2_b64 v0, v[50:51], v[52:53] offset0:64 offset1:66
	v_cvt_pk_bf16_f32 v50, v74, v75
	v_cvt_pk_bf16_f32 v51, v76, v77
	v_cvt_pk_bf16_f32 v52, v78, v79
	v_cvt_pk_bf16_f32 v53, v80, v81
	ds_write2_b64 v0, v[34:35], v[36:37] offset0:72 offset1:74
	v_cvt_pk_bf16_f32 v34, v42, v43
	v_cvt_pk_bf16_f32 v35, v44, v45
	v_cvt_pk_bf16_f32 v36, v46, v47
	v_cvt_pk_bf16_f32 v37, v48, v49
	ds_write2_b64 v0, v[18:19], v[20:21] offset0:80 offset1:82
	v_cvt_pk_bf16_f32 v18, v26, v27
	v_cvt_pk_bf16_f32 v19, v28, v29
	v_cvt_pk_bf16_f32 v20, v30, v31
	v_cvt_pk_bf16_f32 v21, v32, v33
	ds_write2_b64 v0, v[2:3], v[4:5] offset0:88 offset1:90
	v_cvt_pk_bf16_f32 v2, v10, v11
	v_cvt_pk_bf16_f32 v3, v12, v13
	v_cvt_pk_bf16_f32 v4, v14, v15
	v_cvt_pk_bf16_f32 v5, v16, v17
	s_lshl_b64 s[12:13], s[12:13], 1
	ds_write2_b64 v0, v[50:51], v[52:53] offset0:68 offset1:70
	ds_write2_b64 v0, v[34:35], v[36:37] offset0:76 offset1:78
	ds_write2_b64 v0, v[18:19], v[20:21] offset0:84 offset1:86
	ds_write2_b64 v0, v[2:3], v[4:5] offset0:92 offset1:94
	s_waitcnt vmcnt(0) lgkmcnt(0)
	s_barrier
; #define GAS __attribute__((address_space(1)))
;     ...
;   int tid2 = tid; asm volatile("" : "+v"(tid2));
;   if (EPI == 0) {
; #pragma unroll
;     for (int i = 0; i < 16; ++i) {
;       const int id = tid2 + 256 * i, r = id >> 5, c8 = (id & 31) * 8;
;       const u32x4 v = *(const u32x4*)(smem + r * 528 + c8 * 2);
;       *(GAS u32x4*)(ea.out + (size_t)(m0 + r) * ea.ldo + n0 + c8) = v;
;     }
	s_add_u32 s12, s14, s12
	v_lshlrev_b32_e32 v0, 4, v189
	v_and_b32_e32 v0, 0x1f0, v0
	s_addc_u32 s13, s15, s13
	v_add_u32_e32 v10, 16, v0
	v_lshl_add_u64 v[12:13], s[12:13], 0, v[0:1]
	v_ashrrev_i32_e32 v0, 5, v189
	v_mad_u64_u32 v[2:3], s[12:13], v0, s55, v[10:11]
	v_add_u32_e32 v0, s41, v0
	s_movk_i32 s10, 0x600
	v_mad_i64_i32 v[14:15], s[12:13], v0, s10, v[12:13]
	v_add_u32_e32 v0, 0x100, v189
	ds_read_b128 v[2:5], v2
	v_ashrrev_i32_e32 v0, 5, v0
	v_mad_u64_u32 v[6:7], s[12:13], v0, s55, v[10:11]
	ds_read_b128 v[6:9], v6
	v_add_u32_e32 v0, s41, v0
	s_waitcnt lgkmcnt(1)
	global_store_dwordx4 v[14:15], v[2:5], off
	v_readlane_b32 s44, v250, 17
	s_nop 0
	v_mad_i64_i32 v[2:3], s[12:13], v0, s10, v[12:13]
	v_add_u32_e32 v0, 0x200, v189
	v_ashrrev_i32_e32 v0, 5, v0
	s_waitcnt lgkmcnt(0)
	global_store_dwordx4 v[2:3], v[6:9], off
	v_mad_u64_u32 v[2:3], s[12:13], v0, s55, v[10:11]
	v_add_u32_e32 v0, s41, v0
	v_mad_i64_i32 v[14:15], s[12:13], v0, s10, v[12:13]
	v_add_u32_e32 v0, 0x300, v189
	ds_read_b128 v[2:5], v2
	v_ashrrev_i32_e32 v0, 5, v0
	v_mad_u64_u32 v[6:7], s[12:13], v0, s55, v[10:11]
	ds_read_b128 v[6:9], v6
	v_add_u32_e32 v0, s41, v0
	s_waitcnt lgkmcnt(1)
	global_store_dwordx4 v[14:15], v[2:5], off
	s_nop 1
	v_mad_i64_i32 v[2:3], s[12:13], v0, s10, v[12:13]
	v_add_u32_e32 v0, 0x400, v189
	v_ashrrev_i32_e32 v0, 5, v0
	s_waitcnt lgkmcnt(0)
	global_store_dwordx4 v[2:3], v[6:9], off
	v_mad_u64_u32 v[2:3], s[12:13], v0, s55, v[10:11]
	v_add_u32_e32 v0, s41, v0
	v_mad_i64_i32 v[14:15], s[12:13], v0, s10, v[12:13]
	v_add_u32_e32 v0, 0x500, v189
	ds_read_b128 v[2:5], v2
	v_ashrrev_i32_e32 v0, 5, v0
	v_mad_u64_u32 v[6:7], s[12:13], v0, s55, v[10:11]
	ds_read_b128 v[6:9], v6
	v_add_u32_e32 v0, s41, v0
	s_waitcnt lgkmcnt(1)
	global_store_dwordx4 v[14:15], v[2:5], off
	s_nop 1
	v_mad_i64_i32 v[2:3], s[12:13], v0, s10, v[12:13]
	v_add_u32_e32 v0, 0x600, v189
	v_ashrrev_i32_e32 v0, 5, v0
	s_waitcnt lgkmcnt(0)
	global_store_dwordx4 v[2:3], v[6:9], off
	v_mad_u64_u32 v[2:3], s[12:13], v0, s55, v[10:11]
	v_add_u32_e32 v0, s41, v0
	v_mad_i64_i32 v[14:15], s[12:13], v0, s10, v[12:13]
	v_add_u32_e32 v0, 0x700, v189
	ds_read_b128 v[2:5], v2
	v_ashrrev_i32_e32 v0, 5, v0
	v_mad_u64_u32 v[6:7], s[12:13], v0, s55, v[10:11]
	ds_read_b128 v[6:9], v6
	v_add_u32_e32 v0, s41, v0
	s_waitcnt lgkmcnt(1)
	global_store_dwordx4 v[14:15], v[2:5], off
	s_nop 1
	v_mad_i64_i32 v[2:3], s[12:13], v0, s10, v[12:13]
	v_add_u32_e32 v0, 0x800, v189
	v_ashrrev_i32_e32 v0, 5, v0
	s_waitcnt lgkmcnt(0)
	global_store_dwordx4 v[2:3], v[6:9], off
	v_mad_u64_u32 v[2:3], s[12:13], v0, s55, v[10:11]
	v_add_u32_e32 v0, s41, v0
	v_mad_i64_i32 v[14:15], s[12:13], v0, s10, v[12:13]
	v_add_u32_e32 v0, 0x900, v189
	ds_read_b128 v[2:5], v2
	v_ashrrev_i32_e32 v0, 5, v0
	v_mad_u64_u32 v[6:7], s[12:13], v0, s55, v[10:11]
	ds_read_b128 v[6:9], v6
	v_add_u32_e32 v0, s41, v0
	s_waitcnt lgkmcnt(1)
	global_store_dwordx4 v[14:15], v[2:5], off
	s_nop 1
	v_mad_i64_i32 v[2:3], s[12:13], v0, s10, v[12:13]
	v_add_u32_e32 v0, 0xa00, v189
	v_ashrrev_i32_e32 v0, 5, v0
	s_waitcnt lgkmcnt(0)
	global_store_dwordx4 v[2:3], v[6:9], off
	v_mad_u64_u32 v[2:3], s[12:13], v0, s55, v[10:11]
	v_add_u32_e32 v0, s41, v0
	v_mad_i64_i32 v[14:15], s[12:13], v0, s10, v[12:13]
	v_add_u32_e32 v0, 0xb00, v189
	ds_read_b128 v[2:5], v2
	v_ashrrev_i32_e32 v0, 5, v0
	v_mad_u64_u32 v[6:7], s[12:13], v0, s55, v[10:11]
	ds_read_b128 v[6:9], v6
	v_add_u32_e32 v0, s41, v0
	s_waitcnt lgkmcnt(1)
	global_store_dwordx4 v[14:15], v[2:5], off
	s_nop 1
	v_mad_i64_i32 v[2:3], s[12:13], v0, s10, v[12:13]
	v_add_u32_e32 v0, 0xc00, v189
	v_ashrrev_i32_e32 v0, 5, v0
	s_waitcnt lgkmcnt(0)
	global_store_dwordx4 v[2:3], v[6:9], off
	v_mad_u64_u32 v[2:3], s[12:13], v0, s55, v[10:11]
	v_add_u32_e32 v0, s41, v0
	v_mad_i64_i32 v[14:15], s[12:13], v0, s10, v[12:13]
	v_add_u32_e32 v0, 0xd00, v189
	ds_read_b128 v[2:5], v2
	v_ashrrev_i32_e32 v0, 5, v0
	v_mad_u64_u32 v[6:7], s[12:13], v0, s55, v[10:11]
	ds_read_b128 v[6:9], v6
	v_add_u32_e32 v0, s41, v0
	s_waitcnt lgkmcnt(1)
	global_store_dwordx4 v[14:15], v[2:5], off
	s_nop 1
	v_mad_i64_i32 v[2:3], s[12:13], v0, s10, v[12:13]
	v_add_u32_e32 v0, 0xe00, v189
	v_ashrrev_i32_e32 v0, 5, v0
	s_waitcnt lgkmcnt(0)
	global_store_dwordx4 v[2:3], v[6:9], off
	v_mad_u64_u32 v[2:3], s[12:13], v0, s55, v[10:11]
	v_add_u32_e32 v0, s41, v0
	v_mad_i64_i32 v[14:15], s[12:13], v0, s10, v[12:13]
	v_add_u32_e32 v0, 0xf00, v189
	v_ashrrev_i32_e32 v0, 5, v0
	ds_read_b128 v[2:5], v2
	v_mad_u64_u32 v[6:7], s[12:13], v0, s55, v[10:11]
	ds_read_b128 v[6:9], v6
	v_add_u32_e32 v0, s41, v0
	s_waitcnt lgkmcnt(1)
	global_store_dwordx4 v[14:15], v[2:5], off
	s_nop 1
	v_mad_i64_i32 v[2:3], s[12:13], v0, s10, v[12:13]
	s_waitcnt lgkmcnt(0)
	global_store_dwordx4 v[2:3], v[6:9], off
	s_barrier
	s_branch .LBB0_145
